# SGPR-base+VGPR-offset prefetch loads in all 7 GEMM loops (no per-iteration address VALU); store-drain decoupled for MLP1 items
# speedup vs baseline: 1.0372x; 1.0131x over previous
.LBB0_221:
	s_add_i32 s23, s23, s51
	s_cmp_ge_i32 s23, s15
	s_cselect_b64 s[6:7], -1, 0
	s_add_i32 s12, s23, s14
	s_cmp_lt_i32 s23, s15
	s_cselect_b64 s[8:9], -1, 0
	s_and_b64 s[10:11], s[8:9], exec
	s_cselect_b32 s10, s12, 0
	s_mul_hi_u32 s11, s10, 0x38e38e39
	s_lshr_b32 s11, s11, 2
	v_lshl_add_u32 v56, s11, 8, v203
	s_mul_i32 s11, s11, 18
	s_sub_i32 s10, s10, s11
	s_barrier
	s_waitcnt vmcnt(0)
	ds_write_b128 v204, v[16:19]
	s_waitcnt vmcnt(9)
	ds_write_b128 v204, v[20:23] offset:8192
	s_waitcnt vmcnt(7)
	ds_write_b128 v204, v[24:27] offset:16384
	s_waitcnt vmcnt(5)
	ds_write_b128 v204, v[36:39] offset:24576
	s_waitcnt vmcnt(3)
	ds_write_b128 v205, v[28:31]
	s_waitcnt vmcnt(1)
	ds_write_b128 v205, v[40:43] offset:8192
	v_add_co_u32_e32 v16, vcc, s16, v54
	v_lshl_add_u32 v58, s10, 7, v203
	s_nop 0
	v_addc_co_u32_e32 v17, vcc, 0, v55, vcc
	s_mov_b32 s10, 0x60000
	global_load_dwordx4 v[40:43], v[16:17], off offset:256
	global_load_dwordx4 v[28:31], v[54:55], off offset:256
	v_add_co_u32_e32 v16, vcc, s10, v52
	s_mov_b32 s10, 0x40000
	s_nop 0
	v_addc_co_u32_e32 v17, vcc, 0, v53, vcc
	global_load_dwordx4 v[36:39], v[16:17], off offset:256
	v_add_co_u32_e32 v16, vcc, s10, v52
	v_ashrrev_i32_e32 v57, 31, v56
	s_nop 0
	v_addc_co_u32_e32 v17, vcc, 0, v53, vcc
	global_load_dwordx4 v[24:27], v[16:17], off offset:256
	v_add_co_u32_e32 v16, vcc, s16, v52
	v_lshlrev_b64 v[56:57], 11, v[56:57]
	s_nop 0
	v_addc_co_u32_e32 v17, vcc, 0, v53, vcc
	global_load_dwordx4 v[20:23], v[16:17], off offset:256
	s_nop 0
	global_load_dwordx4 v[16:19], v[52:53], off offset:256
	v_lshl_add_u64 v[178:179], v[172:173], 0, v[56:57]
	s_mov_b64 s[10:11], 0x40080
	v_ashrrev_i32_e32 v59, 31, v58
	v_lshl_add_u64 v[184:185], v[178:179], 0, s[10:11]
	s_mov_b64 s[10:11], 0x60080
	v_lshlrev_b64 v[58:59], 11, v[58:59]
	v_lshl_add_u64 v[186:187], v[178:179], 0, s[10:11]
	s_mov_b64 s[10:11], 0x40000
	v_lshl_add_u64 v[180:181], v[174:175], 0, v[58:59]
	v_lshl_add_u64 v[192:193], v[178:179], 0, s[10:11]
	s_mov_b64 s[10:11], 0x60000
	s_nop 0
	v_mov_b32_e32 v48, 0
	s_mov_b32 s27, 0
	v_lshl_add_u64 v[182:183], v[178:179], 0, s[0:1]
	v_lshl_add_u64 v[188:189], v[180:181], 0, s[0:1]
	v_lshl_add_u64 v[190:191], v[178:179], 0, s[2:3]
	v_lshl_add_u64 v[194:195], v[178:179], 0, s[10:11]
	v_lshl_add_u64 v[196:197], v[180:181], 0, s[2:3]
	s_nop 0
	v_mov_b32_e32 v49, v48
	v_mov_b32_e32 v50, v48
	v_mov_b32_e32 v51, v48
	v_mov_b32_e32 v52, v48
	v_mov_b32_e32 v53, v48
	v_mov_b32_e32 v54, v48
	v_mov_b32_e32 v55, v48
	v_mov_b32_e32 v56, v48
	v_mov_b32_e32 v57, v48
	v_mov_b32_e32 v58, v48
	v_mov_b32_e32 v59, v48
	v_mov_b32_e32 v60, v48
	v_mov_b32_e32 v61, v48
	v_mov_b32_e32 v62, v48
	v_mov_b32_e32 v63, v48
	v_mov_b32_e32 v64, v48
	v_mov_b32_e32 v65, v48
	v_mov_b32_e32 v66, v48
	v_mov_b32_e32 v67, v48
	v_mov_b32_e32 v68, v48
	v_mov_b32_e32 v69, v48
	v_mov_b32_e32 v70, v48
	v_mov_b32_e32 v71, v48
	v_mov_b32_e32 v72, v48
	v_mov_b32_e32 v73, v48
	v_mov_b32_e32 v74, v48
	v_mov_b32_e32 v75, v48
	v_mov_b32_e32 v76, v48
	v_mov_b32_e32 v77, v48
	v_mov_b32_e32 v78, v48
	v_mov_b32_e32 v79, v48
	v_mov_b32_e32 v80, v48
	v_mov_b32_e32 v81, v48
	v_mov_b32_e32 v82, v48
	v_mov_b32_e32 v83, v48
	v_mov_b32_e32 v84, v48
	v_mov_b32_e32 v85, v48
	v_mov_b32_e32 v86, v48
	v_mov_b32_e32 v87, v48
	v_mov_b32_e32 v88, v48
	v_mov_b32_e32 v89, v48
	v_mov_b32_e32 v90, v48
	v_mov_b32_e32 v91, v48
	v_mov_b32_e32 v92, v48
	v_mov_b32_e32 v93, v48
	v_mov_b32_e32 v94, v48
	v_mov_b32_e32 v95, v48
	v_mov_b32_e32 v96, v48
	v_mov_b32_e32 v97, v48
	v_mov_b32_e32 v98, v48
	v_mov_b32_e32 v99, v48
	v_mov_b32_e32 v100, v48
	v_mov_b32_e32 v101, v48
	v_mov_b32_e32 v102, v48
	v_mov_b32_e32 v103, v48
	v_mov_b32_e32 v104, v48
	v_mov_b32_e32 v105, v48
	v_mov_b32_e32 v106, v48
	v_mov_b32_e32 v107, v48
	v_mov_b32_e32 v108, v48
	v_mov_b32_e32 v109, v48
	v_mov_b32_e32 v110, v48
	v_mov_b32_e32 v111, v48
	s_lshl_b32 s98, s25, 11
	s_add_u32 s98, s72, s98
	s_addc_u32 s99, s73, 0
	s_add_u32 s98, s98, 0x2800000
	s_addc_u32 s99, s99, 0
	s_lshl_b32 s100, s26, 11
	s_add_u32 s100, s72, s100
	s_addc_u32 s101, s73, 0
	s_add_u32 s100, s100, 0x400000
	s_addc_u32 s101, s101, 0
	v_lshl_add_u32 v200, v203, 11, v176
	v_add_u32_e32 v201, 0x20000, v200
	v_add_u32_e32 v198, 0x40000, v200
	v_add_u32_e32 v199, 0x60000, v200
	s_branch .LBB0_223

.Lmyafe__227:
	s_andn2_b64 vcc, exec, s[10:11]
	s_cbranch_vccnz .Lmyafe__229
	global_load_dwordx4 v[0:3], v200, s[98:99] offset:384
	global_load_dwordx4 v[4:7], v201, s[98:99] offset:384
	global_load_dwordx4 v[8:11], v198, s[98:99] offset:384
	global_load_dwordx4 v[12:15], v199, s[98:99] offset:384
	global_load_dwordx4 v[32:35], v200, s[100:101] offset:384
	global_load_dwordx4 v[44:47], v201, s[100:101] offset:384

.Lmyaso__234:
	s_andn2_b64 vcc, exec, s[12:13]
	s_cbranch_vccnz .Lmya_ocont
	global_load_dwordx4 v[16:19], v200, s[98:99] offset:512
	global_load_dwordx4 v[20:23], v201, s[98:99] offset:512
	global_load_dwordx4 v[24:27], v198, s[98:99] offset:512
	global_load_dwordx4 v[36:39], v199, s[98:99] offset:512
	global_load_dwordx4 v[28:31], v200, s[100:101] offset:512
	global_load_dwordx4 v[40:43], v201, s[100:101] offset:512
.Lmya_ocont:
	v_mfma_f32_16x16x32_bf16 v[76:79], v[152:155], v[160:163], v[76:79]
	v_mfma_f32_16x16x32_bf16 v[72:75], v[152:155], v[164:167], v[72:75]
	v_mfma_f32_16x16x32_bf16 v[68:71], v[152:155], v[228:231], v[68:71]
	v_mfma_f32_16x16x32_bf16 v[64:67], v[152:155], v[232:235], v[64:67]
	v_mfma_f32_16x16x32_bf16 v[60:63], v[156:159], v[160:163], v[60:63]
	v_mfma_f32_16x16x32_bf16 v[56:59], v[156:159], v[164:167], v[56:59]
	v_mfma_f32_16x16x32_bf16 v[52:55], v[156:159], v[228:231], v[52:55]
	v_mfma_f32_16x16x32_bf16 v[48:51], v[156:159], v[232:235], v[48:51]
	s_waitcnt lgkmcnt(0)
	v_mfma_f32_16x16x32_bf16 v[108:111], v[112:115], v[128:131], v[108:111]
	ds_read_b128 v[144:147], v208 offset:32768
	v_mfma_f32_16x16x32_bf16 v[104:107], v[112:115], v[132:135], v[104:107]
	ds_read_b128 v[148:151], v208 offset:34816
	v_mfma_f32_16x16x32_bf16 v[100:103], v[112:115], v[136:139], v[100:103]
	ds_read_b128 v[152:155], v208 offset:36864
	v_mfma_f32_16x16x32_bf16 v[96:99], v[112:115], v[140:143], v[96:99]
	ds_read_b128 v[156:159], v208 offset:38912
	v_mfma_f32_16x16x32_bf16 v[92:95], v[116:119], v[128:131], v[92:95]
	ds_read_b128 v[160:163], v212
	v_mfma_f32_16x16x32_bf16 v[88:91], v[116:119], v[132:135], v[88:91]
	ds_read_b128 v[164:167], v212 offset:2048
	v_mfma_f32_16x16x32_bf16 v[84:87], v[116:119], v[136:139], v[84:87]
	ds_read_b128 v[228:231], v212 offset:4096
	v_mfma_f32_16x16x32_bf16 v[80:83], v[116:119], v[140:143], v[80:83]
	ds_read_b128 v[232:235], v212 offset:6144
	v_mfma_f32_16x16x32_bf16 v[76:79], v[120:123], v[128:131], v[76:79]
	v_mfma_f32_16x16x32_bf16 v[72:75], v[120:123], v[132:135], v[72:75]
	v_mfma_f32_16x16x32_bf16 v[68:71], v[120:123], v[136:139], v[68:71]
	v_mfma_f32_16x16x32_bf16 v[64:67], v[120:123], v[140:143], v[64:67]
	v_mfma_f32_16x16x32_bf16 v[60:63], v[124:127], v[128:131], v[60:63]
	v_mfma_f32_16x16x32_bf16 v[56:59], v[124:127], v[132:135], v[56:59]
	v_mfma_f32_16x16x32_bf16 v[52:55], v[124:127], v[136:139], v[52:55]
	v_mfma_f32_16x16x32_bf16 v[48:51], v[124:127], v[140:143], v[48:51]
	s_add_i32 s27, s27, 2
	s_add_u32 s100, s100, 0x100
	s_addc_u32 s101, s101, 0
	s_add_u32 s98, s98, 0x100
	s_addc_u32 s99, s99, 0
	s_branch .Lmya_even
.Lmya_oddlast:
	v_mfma_f32_16x16x32_bf16 v[108:111], v[144:147], v[160:163], v[108:111]
	v_mfma_f32_16x16x32_bf16 v[104:107], v[144:147], v[164:167], v[104:107]
	v_mfma_f32_16x16x32_bf16 v[100:103], v[144:147], v[228:231], v[100:103]
	v_mfma_f32_16x16x32_bf16 v[96:99], v[144:147], v[232:235], v[96:99]
	v_mfma_f32_16x16x32_bf16 v[92:95], v[148:151], v[160:163], v[92:95]
	v_mfma_f32_16x16x32_bf16 v[88:91], v[148:151], v[164:167], v[88:91]
	v_mfma_f32_16x16x32_bf16 v[84:87], v[148:151], v[228:231], v[84:87]
	v_mfma_f32_16x16x32_bf16 v[80:83], v[148:151], v[232:235], v[80:83]
	v_mfma_f32_16x16x32_bf16 v[76:79], v[152:155], v[160:163], v[76:79]
	v_mfma_f32_16x16x32_bf16 v[72:75], v[152:155], v[164:167], v[72:75]
	v_mfma_f32_16x16x32_bf16 v[68:71], v[152:155], v[228:231], v[68:71]
	v_mfma_f32_16x16x32_bf16 v[64:67], v[152:155], v[232:235], v[64:67]
	v_mfma_f32_16x16x32_bf16 v[60:63], v[156:159], v[160:163], v[60:63]
	v_mfma_f32_16x16x32_bf16 v[56:59], v[156:159], v[164:167], v[56:59]
	v_mfma_f32_16x16x32_bf16 v[52:55], v[156:159], v[228:231], v[52:55]
	v_mfma_f32_16x16x32_bf16 v[48:51], v[156:159], v[232:235], v[48:51]
	s_waitcnt lgkmcnt(0)
	v_mfma_f32_16x16x32_bf16 v[108:111], v[112:115], v[128:131], v[108:111]
	ds_read_b128 v[144:147], v208 offset:32768
	v_mfma_f32_16x16x32_bf16 v[104:107], v[112:115], v[132:135], v[104:107]
	ds_read_b128 v[148:151], v208 offset:34816
	v_mfma_f32_16x16x32_bf16 v[100:103], v[112:115], v[136:139], v[100:103]
	ds_read_b128 v[152:155], v208 offset:36864
	v_mfma_f32_16x16x32_bf16 v[96:99], v[112:115], v[140:143], v[96:99]
	ds_read_b128 v[156:159], v208 offset:38912
	v_mfma_f32_16x16x32_bf16 v[92:95], v[116:119], v[128:131], v[92:95]
	ds_read_b128 v[160:163], v212
	v_mfma_f32_16x16x32_bf16 v[88:91], v[116:119], v[132:135], v[88:91]
	ds_read_b128 v[164:167], v212 offset:2048
	v_mfma_f32_16x16x32_bf16 v[84:87], v[116:119], v[136:139], v[84:87]
	ds_read_b128 v[228:231], v212 offset:4096
	v_mfma_f32_16x16x32_bf16 v[80:83], v[116:119], v[140:143], v[80:83]
	ds_read_b128 v[232:235], v212 offset:6144
	v_mfma_f32_16x16x32_bf16 v[76:79], v[120:123], v[128:131], v[76:79]
	v_mfma_f32_16x16x32_bf16 v[72:75], v[120:123], v[132:135], v[72:75]
	v_mfma_f32_16x16x32_bf16 v[68:71], v[120:123], v[136:139], v[68:71]
	v_mfma_f32_16x16x32_bf16 v[64:67], v[120:123], v[140:143], v[64:67]
	v_mfma_f32_16x16x32_bf16 v[60:63], v[124:127], v[128:131], v[60:63]
	v_mfma_f32_16x16x32_bf16 v[56:59], v[124:127], v[132:135], v[56:59]
	v_mfma_f32_16x16x32_bf16 v[52:55], v[124:127], v[136:139], v[52:55]
	v_mfma_f32_16x16x32_bf16 v[48:51], v[124:127], v[140:143], v[48:51]
	s_add_i32 s27, s27, 2
	s_add_u32 s100, s100, 0x100
	s_addc_u32 s101, s101, 0
	s_add_u32 s98, s98, 0x100
	s_addc_u32 s99, s99, 0
	s_waitcnt lgkmcnt(0)
	v_mfma_f32_16x16x32_bf16 v[108:111], v[144:147], v[160:163], v[108:111]
	v_mfma_f32_16x16x32_bf16 v[104:107], v[144:147], v[164:167], v[104:107]
	v_mfma_f32_16x16x32_bf16 v[100:103], v[144:147], v[228:231], v[100:103]
	v_mfma_f32_16x16x32_bf16 v[96:99], v[144:147], v[232:235], v[96:99]
	v_mfma_f32_16x16x32_bf16 v[92:95], v[148:151], v[160:163], v[92:95]
	v_mfma_f32_16x16x32_bf16 v[88:91], v[148:151], v[164:167], v[88:91]
	v_mfma_f32_16x16x32_bf16 v[84:87], v[148:151], v[228:231], v[84:87]
	v_mfma_f32_16x16x32_bf16 v[80:83], v[148:151], v[232:235], v[80:83]
	v_mfma_f32_16x16x32_bf16 v[76:79], v[152:155], v[160:163], v[76:79]
	v_mfma_f32_16x16x32_bf16 v[72:75], v[152:155], v[164:167], v[72:75]
	v_mfma_f32_16x16x32_bf16 v[68:71], v[152:155], v[228:231], v[68:71]
	v_mfma_f32_16x16x32_bf16 v[64:67], v[152:155], v[232:235], v[64:67]
	v_mfma_f32_16x16x32_bf16 v[60:63], v[156:159], v[160:163], v[60:63]
	v_mfma_f32_16x16x32_bf16 v[56:59], v[156:159], v[164:167], v[56:59]
	v_mfma_f32_16x16x32_bf16 v[52:55], v[156:159], v[228:231], v[52:55]
	v_mfma_f32_16x16x32_bf16 v[48:51], v[156:159], v[232:235], v[48:51]
	s_and_b64 vcc, exec, s[10:11]
	s_nop 7
	s_branch .LBB0_236

.LBB0_631:
	s_barrier
	s_waitcnt vmcnt(11)
	ds_write_b128 v204, v[36:39]
	s_waitcnt vmcnt(9)
	ds_write_b128 v204, v[44:47] offset:8192
	s_waitcnt vmcnt(7)
	ds_write_b128 v204, v[32:35] offset:16384
	s_waitcnt vmcnt(5)
	ds_write_b128 v204, v[40:43] offset:24576
	s_waitcnt vmcnt(3)
	ds_write_b128 v205, v[20:23]
	s_waitcnt vmcnt(1)
	ds_write_b128 v205, v[28:31] offset:8192
	v_add_co_u32_e32 v20, vcc, s23, v50
	s_and_b32 s0, s19, 0x380
	s_nop 0
	v_addc_co_u32_e32 v21, vcc, 0, v51, vcc
	v_add_co_u32_e32 v32, vcc, 0x60000, v48
	global_load_dwordx4 v[28:31], v[20:21], off offset:256
	s_nop 0
	global_load_dwordx4 v[20:23], v[50:51], off offset:256
	v_addc_co_u32_e32 v33, vcc, 0, v49, vcc
	global_load_dwordx4 v[40:43], v[32:33], off offset:256
	v_add_co_u32_e32 v32, vcc, 0x40000, v48
	v_add_u32_e32 v52, s0, v203
	s_nop 0
	v_addc_co_u32_e32 v33, vcc, 0, v49, vcc
	v_add_co_u32_e32 v36, vcc, 0x20000, v48
	global_load_dwordx4 v[32:35], v[32:33], off offset:256
	s_nop 0
	v_addc_co_u32_e32 v37, vcc, 0, v49, vcc
	global_load_dwordx4 v[44:47], v[36:37], off offset:256
	s_nop 0
	global_load_dwordx4 v[36:39], v[48:49], off offset:256
	v_ashrrev_i32_e32 v53, 31, v52
	s_and_b32 s0, s21, 0x7fffff00
	s_add_i32 s44, s44, s51
	v_lshlrev_b64 v[52:53], 11, v[52:53]
	s_cmp_ge_i32 s44, s33
	s_nop 0
	v_add_u32_e32 v52, s0, v203
	s_cselect_b64 s[0:1], -1, 0
	s_add_i32 s16, s44, s29
	s_cmp_lt_i32 s44, s33
	s_cselect_b64 s[12:13], -1, 0
	s_and_b64 s[14:15], s[12:13], exec
	s_cselect_b32 s14, s16, 0
	v_ashrrev_i32_e32 v53, 31, v52
	s_lshl_b32 s15, s14, 5
	v_lshlrev_b64 v[52:53], 11, v[52:53]
	s_and_b32 s15, s15, 0x7fffff00
	s_nop 0
	v_add_u32_e32 v52, s15, v203
	s_lshl_b32 s14, s14, 7
	v_ashrrev_i32_e32 v53, 31, v52
	s_and_b32 s14, s14, 0x380
	v_lshlrev_b64 v[52:53], 11, v[52:53]
	v_add_u32_e32 v54, s14, v203
	v_ashrrev_i32_e32 v55, 31, v54
	v_lshl_add_u64 v[182:183], v[172:173], 0, v[52:53]
	s_mov_b64 s[14:15], 0x40080
	v_lshlrev_b64 v[54:55], 11, v[54:55]
	v_lshl_add_u64 v[188:189], v[182:183], 0, s[14:15]
	s_mov_b64 s[14:15], 0x60080
	v_lshl_add_u64 v[184:185], v[174:175], 0, v[54:55]
	v_lshl_add_u64 v[190:191], v[182:183], 0, s[14:15]
	s_mov_b64 s[14:15], 0x40000
	v_mov_b32_e32 v48, 0
	s_mov_b32 s47, 0
	v_lshl_add_u64 v[186:187], v[182:183], 0, s[2:3]
	v_lshl_add_u64 v[192:193], v[184:185], 0, s[2:3]
	v_lshl_add_u64 v[194:195], v[182:183], 0, s[4:5]
	v_lshl_add_u64 v[196:197], v[182:183], 0, s[14:15]
	v_lshl_add_u64 v[198:199], v[182:183], 0, s[6:7]
	v_lshl_add_u64 v[200:201], v[184:185], 0, s[4:5]
	v_mov_b32_e32 v49, v48
	v_mov_b32_e32 v50, v48
	v_mov_b32_e32 v51, v48
	v_mov_b32_e32 v52, v48
	v_mov_b32_e32 v53, v48
	v_mov_b32_e32 v54, v48
	v_mov_b32_e32 v55, v48
	v_mov_b32_e32 v56, v48
	v_mov_b32_e32 v57, v48
	v_mov_b32_e32 v58, v48
	v_mov_b32_e32 v59, v48
	v_mov_b32_e32 v60, v48
	v_mov_b32_e32 v61, v48
	v_mov_b32_e32 v62, v48
	v_mov_b32_e32 v63, v48
	v_mov_b32_e32 v64, v48
	v_mov_b32_e32 v65, v48
	v_mov_b32_e32 v66, v48
	v_mov_b32_e32 v67, v48
	v_mov_b32_e32 v68, v48
	v_mov_b32_e32 v69, v48
	v_mov_b32_e32 v70, v48
	v_mov_b32_e32 v71, v48
	v_mov_b32_e32 v72, v48
	v_mov_b32_e32 v73, v48
	v_mov_b32_e32 v74, v48
	v_mov_b32_e32 v75, v48
	v_mov_b32_e32 v76, v48
	v_mov_b32_e32 v77, v48
	v_mov_b32_e32 v78, v48
	v_mov_b32_e32 v79, v48
	v_mov_b32_e32 v80, v48
	v_mov_b32_e32 v81, v48
	v_mov_b32_e32 v82, v48
	v_mov_b32_e32 v83, v48
	v_mov_b32_e32 v84, v48
	v_mov_b32_e32 v85, v48
	v_mov_b32_e32 v86, v48
	v_mov_b32_e32 v87, v48
	v_mov_b32_e32 v88, v48
	v_mov_b32_e32 v89, v48
	v_mov_b32_e32 v90, v48
	v_mov_b32_e32 v91, v48
	v_mov_b32_e32 v92, v48
	v_mov_b32_e32 v93, v48
	v_mov_b32_e32 v94, v48
	v_mov_b32_e32 v95, v48
	v_mov_b32_e32 v96, v48
	v_mov_b32_e32 v97, v48
	v_mov_b32_e32 v98, v48
	v_mov_b32_e32 v99, v48
	v_mov_b32_e32 v100, v48
	v_mov_b32_e32 v101, v48
	v_mov_b32_e32 v102, v48
	v_mov_b32_e32 v103, v48
	v_mov_b32_e32 v104, v48
	v_mov_b32_e32 v105, v48
	v_mov_b32_e32 v106, v48
	v_mov_b32_e32 v107, v48
	v_mov_b32_e32 v108, v48
	v_mov_b32_e32 v109, v48
	v_mov_b32_e32 v110, v48
	v_mov_b32_e32 v111, v48
	s_lshl_b32 s98, s45, 11
	s_add_u32 s98, s76, s98
	s_addc_u32 s99, s77, 0
	s_add_u32 s98, s98, 0xac00000
	s_addc_u32 s99, s99, 0
	s_lshl_b32 s100, s46, 11
	s_add_u32 s100, s76, s100
	s_addc_u32 s101, s77, 0
	s_add_u32 s100, s100, 0x880000
	s_addc_u32 s101, s101, 0
	v_lshl_add_u32 v180, v203, 11, v176
	v_add_u32_e32 v181, 0x20000, v180
	v_add_u32_e32 v178, 0x40000, v180
	v_add_u32_e32 v179, 0x60000, v180
	s_branch .LBB0_633

.Lmybfe__637:
	s_andn2_b64 vcc, exec, s[14:15]
	s_cbranch_vccnz .Lmybfe__639
	global_load_dwordx4 v[0:3], v180, s[98:99] offset:384
	global_load_dwordx4 v[4:7], v181, s[98:99] offset:384
	global_load_dwordx4 v[8:11], v178, s[98:99] offset:384
	global_load_dwordx4 v[12:15], v179, s[98:99] offset:384
	global_load_dwordx4 v[16:19], v180, s[100:101] offset:384
	global_load_dwordx4 v[24:27], v181, s[100:101] offset:384

.Lmybso__644:
	s_andn2_b64 vcc, exec, s[16:17]
	s_cbranch_vccnz .Lmyb_ocont
	global_load_dwordx4 v[36:39], v180, s[98:99] offset:512
	global_load_dwordx4 v[44:47], v181, s[98:99] offset:512
	global_load_dwordx4 v[32:35], v178, s[98:99] offset:512
	global_load_dwordx4 v[40:43], v179, s[98:99] offset:512
	global_load_dwordx4 v[20:23], v180, s[100:101] offset:512
	global_load_dwordx4 v[28:31], v181, s[100:101] offset:512
.Lmyb_ocont:
	v_mfma_f32_16x16x32_bf16 v[76:79], v[152:155], v[160:163], v[76:79]
	v_mfma_f32_16x16x32_bf16 v[72:75], v[152:155], v[164:167], v[72:75]
	v_mfma_f32_16x16x32_bf16 v[68:71], v[152:155], v[216:219], v[68:71]
	v_mfma_f32_16x16x32_bf16 v[64:67], v[152:155], v[228:231], v[64:67]
	v_mfma_f32_16x16x32_bf16 v[60:63], v[156:159], v[160:163], v[60:63]
	v_mfma_f32_16x16x32_bf16 v[56:59], v[156:159], v[164:167], v[56:59]
	v_mfma_f32_16x16x32_bf16 v[52:55], v[156:159], v[216:219], v[52:55]
	v_mfma_f32_16x16x32_bf16 v[48:51], v[156:159], v[228:231], v[48:51]
	s_waitcnt lgkmcnt(0)
	v_mfma_f32_16x16x32_bf16 v[108:111], v[112:115], v[128:131], v[108:111]
	ds_read_b128 v[144:147], v208 offset:32768
	v_mfma_f32_16x16x32_bf16 v[104:107], v[112:115], v[132:135], v[104:107]
	ds_read_b128 v[148:151], v208 offset:34816
	v_mfma_f32_16x16x32_bf16 v[100:103], v[112:115], v[136:139], v[100:103]
	ds_read_b128 v[152:155], v208 offset:36864
	v_mfma_f32_16x16x32_bf16 v[96:99], v[112:115], v[140:143], v[96:99]
	ds_read_b128 v[156:159], v208 offset:38912
	v_mfma_f32_16x16x32_bf16 v[92:95], v[116:119], v[128:131], v[92:95]
	ds_read_b128 v[160:163], v212
	v_mfma_f32_16x16x32_bf16 v[88:91], v[116:119], v[132:135], v[88:91]
	ds_read_b128 v[164:167], v212 offset:2048
	v_mfma_f32_16x16x32_bf16 v[84:87], v[116:119], v[136:139], v[84:87]
	ds_read_b128 v[216:219], v212 offset:4096
	v_mfma_f32_16x16x32_bf16 v[80:83], v[116:119], v[140:143], v[80:83]
	ds_read_b128 v[228:231], v212 offset:6144
	v_mfma_f32_16x16x32_bf16 v[76:79], v[120:123], v[128:131], v[76:79]
	v_mfma_f32_16x16x32_bf16 v[72:75], v[120:123], v[132:135], v[72:75]
	v_mfma_f32_16x16x32_bf16 v[68:71], v[120:123], v[136:139], v[68:71]
	v_mfma_f32_16x16x32_bf16 v[64:67], v[120:123], v[140:143], v[64:67]
	v_mfma_f32_16x16x32_bf16 v[60:63], v[124:127], v[128:131], v[60:63]
	v_mfma_f32_16x16x32_bf16 v[56:59], v[124:127], v[132:135], v[56:59]
	v_mfma_f32_16x16x32_bf16 v[52:55], v[124:127], v[136:139], v[52:55]
	v_mfma_f32_16x16x32_bf16 v[48:51], v[124:127], v[140:143], v[48:51]
	s_add_i32 s47, s47, 2
	s_add_u32 s100, s100, 0x100
	s_addc_u32 s101, s101, 0
	s_add_u32 s98, s98, 0x100
	s_addc_u32 s99, s99, 0
	s_branch .Lmyb_even
.Lmyb_oddlast:
	v_mfma_f32_16x16x32_bf16 v[108:111], v[144:147], v[160:163], v[108:111]
	v_mfma_f32_16x16x32_bf16 v[104:107], v[144:147], v[164:167], v[104:107]
	v_mfma_f32_16x16x32_bf16 v[100:103], v[144:147], v[216:219], v[100:103]
	v_mfma_f32_16x16x32_bf16 v[96:99], v[144:147], v[228:231], v[96:99]
	v_mfma_f32_16x16x32_bf16 v[92:95], v[148:151], v[160:163], v[92:95]
	v_mfma_f32_16x16x32_bf16 v[88:91], v[148:151], v[164:167], v[88:91]
	v_mfma_f32_16x16x32_bf16 v[84:87], v[148:151], v[216:219], v[84:87]
	v_mfma_f32_16x16x32_bf16 v[80:83], v[148:151], v[228:231], v[80:83]
	v_mfma_f32_16x16x32_bf16 v[76:79], v[152:155], v[160:163], v[76:79]
	v_mfma_f32_16x16x32_bf16 v[72:75], v[152:155], v[164:167], v[72:75]
	v_mfma_f32_16x16x32_bf16 v[68:71], v[152:155], v[216:219], v[68:71]
	v_mfma_f32_16x16x32_bf16 v[64:67], v[152:155], v[228:231], v[64:67]
	v_mfma_f32_16x16x32_bf16 v[60:63], v[156:159], v[160:163], v[60:63]
	v_mfma_f32_16x16x32_bf16 v[56:59], v[156:159], v[164:167], v[56:59]
	v_mfma_f32_16x16x32_bf16 v[52:55], v[156:159], v[216:219], v[52:55]
	v_mfma_f32_16x16x32_bf16 v[48:51], v[156:159], v[228:231], v[48:51]
	s_waitcnt lgkmcnt(0)
	v_mfma_f32_16x16x32_bf16 v[108:111], v[112:115], v[128:131], v[108:111]
	ds_read_b128 v[144:147], v208 offset:32768
	v_mfma_f32_16x16x32_bf16 v[104:107], v[112:115], v[132:135], v[104:107]
	ds_read_b128 v[148:151], v208 offset:34816
	v_mfma_f32_16x16x32_bf16 v[100:103], v[112:115], v[136:139], v[100:103]
	ds_read_b128 v[152:155], v208 offset:36864
	v_mfma_f32_16x16x32_bf16 v[96:99], v[112:115], v[140:143], v[96:99]
	ds_read_b128 v[156:159], v208 offset:38912
	v_mfma_f32_16x16x32_bf16 v[92:95], v[116:119], v[128:131], v[92:95]
	ds_read_b128 v[160:163], v212
	v_mfma_f32_16x16x32_bf16 v[88:91], v[116:119], v[132:135], v[88:91]
	ds_read_b128 v[164:167], v212 offset:2048
	v_mfma_f32_16x16x32_bf16 v[84:87], v[116:119], v[136:139], v[84:87]
	ds_read_b128 v[216:219], v212 offset:4096
	v_mfma_f32_16x16x32_bf16 v[80:83], v[116:119], v[140:143], v[80:83]
	ds_read_b128 v[228:231], v212 offset:6144
	v_mfma_f32_16x16x32_bf16 v[76:79], v[120:123], v[128:131], v[76:79]
	v_mfma_f32_16x16x32_bf16 v[72:75], v[120:123], v[132:135], v[72:75]
	v_mfma_f32_16x16x32_bf16 v[68:71], v[120:123], v[136:139], v[68:71]
	v_mfma_f32_16x16x32_bf16 v[64:67], v[120:123], v[140:143], v[64:67]
	v_mfma_f32_16x16x32_bf16 v[60:63], v[124:127], v[128:131], v[60:63]
	v_mfma_f32_16x16x32_bf16 v[56:59], v[124:127], v[132:135], v[56:59]
	v_mfma_f32_16x16x32_bf16 v[52:55], v[124:127], v[136:139], v[52:55]
	v_mfma_f32_16x16x32_bf16 v[48:51], v[124:127], v[140:143], v[48:51]
	s_add_i32 s47, s47, 2
	s_add_u32 s100, s100, 0x100
	s_addc_u32 s101, s101, 0
	s_add_u32 s98, s98, 0x100
	s_addc_u32 s99, s99, 0
	s_waitcnt lgkmcnt(0)
	v_mfma_f32_16x16x32_bf16 v[108:111], v[144:147], v[160:163], v[108:111]
	v_mfma_f32_16x16x32_bf16 v[104:107], v[144:147], v[164:167], v[104:107]
	v_mfma_f32_16x16x32_bf16 v[100:103], v[144:147], v[216:219], v[100:103]
	v_mfma_f32_16x16x32_bf16 v[96:99], v[144:147], v[228:231], v[96:99]
	v_mfma_f32_16x16x32_bf16 v[92:95], v[148:151], v[160:163], v[92:95]
	v_mfma_f32_16x16x32_bf16 v[88:91], v[148:151], v[164:167], v[88:91]
	v_mfma_f32_16x16x32_bf16 v[84:87], v[148:151], v[216:219], v[84:87]
	v_mfma_f32_16x16x32_bf16 v[80:83], v[148:151], v[228:231], v[80:83]
	v_mfma_f32_16x16x32_bf16 v[76:79], v[152:155], v[160:163], v[76:79]
	v_mfma_f32_16x16x32_bf16 v[72:75], v[152:155], v[164:167], v[72:75]
	v_mfma_f32_16x16x32_bf16 v[68:71], v[152:155], v[216:219], v[68:71]
	v_mfma_f32_16x16x32_bf16 v[64:67], v[152:155], v[228:231], v[64:67]
	v_mfma_f32_16x16x32_bf16 v[60:63], v[156:159], v[160:163], v[60:63]
	v_mfma_f32_16x16x32_bf16 v[56:59], v[156:159], v[164:167], v[56:59]
	v_mfma_f32_16x16x32_bf16 v[52:55], v[156:159], v[216:219], v[52:55]
	v_mfma_f32_16x16x32_bf16 v[48:51], v[156:159], v[228:231], v[48:51]
	s_and_b64 vcc, exec, s[14:15]
	s_nop 7
	s_branch .LBB0_646

.Lswz_c1:
	v_add_u32_e32 v48, s35, v203
	v_add_u32_e32 v50, s37, v203
	v_ashrrev_i32_e32 v49, 31, v48
	v_ashrrev_i32_e32 v51, 31, v50
	v_lshlrev_b64 v[48:49], 11, v[48:49]
	v_lshlrev_b64 v[50:51], 11, v[50:51]
	v_lshl_add_u64 v[48:49], v[172:173], 0, v[48:49]
	v_lshl_add_u64 v[50:51], v[174:175], 0, v[50:51]
	s_and_b64 vcc, exec, s[16:17]
	s_cbranch_vccnz .Lprimed_c
	s_waitcnt vmcnt(62)
	v_add_co_u32_e32 v4, vcc, 0x20000, v48
	s_nop 1
	v_addc_co_u32_e32 v5, vcc, 0, v49, vcc
	v_add_co_u32_e32 v8, vcc, 0x40000, v48
	s_nop 1
	v_addc_co_u32_e32 v9, vcc, 0, v49, vcc
	v_add_co_u32_e32 v16, vcc, 0x60000, v48
	s_nop 1
	v_addc_co_u32_e32 v17, vcc, 0, v49, vcc
	v_add_co_u32_e32 v36, vcc, 0x20000, v50
	s_nop 1
	v_addc_co_u32_e32 v37, vcc, 0, v51, vcc
	global_load_dwordx4 v[12:15], v[48:49], off
	global_load_dwordx4 v[0:3], v[48:49], off offset:128
	global_load_dwordx4 v[20:23], v[4:5], off
	s_nop 0
	global_load_dwordx4 v[4:7], v[4:5], off offset:128
	s_nop 0
	global_load_dwordx4 v[32:35], v[8:9], off
	s_nop 0
	global_load_dwordx4 v[8:11], v[8:9], off offset:128
	s_nop 0
	global_load_dwordx4 v[24:27], v[16:17], off
	s_nop 0
	global_load_dwordx4 v[16:19], v[16:17], off offset:128
	s_nop 0
	global_load_dwordx4 v[44:47], v[50:51], off
	global_load_dwordx4 v[28:31], v[50:51], off offset:128
	global_load_dwordx4 v[40:43], v[36:37], off
	s_nop 0
	global_load_dwordx4 v[36:39], v[36:37], off offset:128
	s_branch .LBB0_772
.Lprimed_c:
	s_barrier
	s_waitcnt vmcnt(8)
	ds_write_b128 v204, v[12:15]
	ds_write_b128 v204, v[20:23] offset:8192
	ds_write_b128 v204, v[32:35] offset:16384
	ds_write_b128 v204, v[24:27] offset:24576
	ds_write_b128 v205, v[44:47]
	ds_write_b128 v205, v[40:43] offset:8192
	s_branch .Lafterw_c
.LBB0_772:
	s_barrier
	s_waitcnt vmcnt(11)
	ds_write_b128 v204, v[12:15]
	s_waitcnt vmcnt(9)
	ds_write_b128 v204, v[20:23] offset:8192
	s_waitcnt vmcnt(7)
	ds_write_b128 v204, v[32:35] offset:16384
	s_waitcnt vmcnt(5)
	ds_write_b128 v204, v[24:27] offset:24576
	s_waitcnt vmcnt(3)
	ds_write_b128 v205, v[44:47]
	s_waitcnt vmcnt(0)
	ds_write_b128 v205, v[40:43] offset:8192
.Lafterw_c:
	v_add_co_u32_e32 v12, vcc, s30, v50
	s_mov_b32 s14, s37
	s_nop 0
	v_addc_co_u32_e32 v13, vcc, 0, v51, vcc
	v_add_co_u32_e32 v14, vcc, 0x60000, v48
	v_add_u32_e32 v52, s14, v203
	s_nop 0
	v_addc_co_u32_e32 v15, vcc, 0, v49, vcc
	global_load_dwordx4 v[40:43], v[12:13], off offset:256
	global_load_dwordx4 v[24:27], v[14:15], off offset:256
	v_add_co_u32_e32 v12, vcc, 0x40000, v48
	v_ashrrev_i32_e32 v53, 31, v52
	s_nop 0
	v_addc_co_u32_e32 v13, vcc, 0, v49, vcc
	v_add_co_u32_e32 v14, vcc, 0x20000, v48
	s_mov_b32 s14, s35
	s_nop 0
	v_addc_co_u32_e32 v15, vcc, 0, v49, vcc
	global_load_dwordx4 v[32:35], v[12:13], off offset:256
	global_load_dwordx4 v[20:23], v[14:15], off offset:256
	global_load_dwordx4 v[44:47], v[50:51], off offset:256
	s_nop 0
	global_load_dwordx4 v[12:15], v[48:49], off offset:256
	s_add_i32 s34, s34, s51
	v_lshlrev_b64 v[52:53], 11, v[52:53]
	s_cmp_ge_i32 s34, s23
	s_nop 0
	v_add_u32_e32 v52, s14, v203
	s_cselect_b64 s[14:15], -1, 0
	s_add_i32 s20, s34, s22
	s_cmp_lt_i32 s34, s23
	s_cselect_b64 s[16:17], -1, 0
	s_and_b64 s[18:19], s[16:17], exec
	s_cselect_b32 s18, s20, 0
	v_ashrrev_i32_e32 v53, 31, v52
	v_lshlrev_b64 v[52:53], 11, v[52:53]
	s_mov_b32 s100, s18
	s_lshr_b32 s98, s100, 7
	s_lshl_b32 s98, s98, 10
	s_and_b32 s99, s100, 3
	s_lshl_b32 s99, s99, 8
	s_or_b32 s19, s98, s99
	s_lshl_b32 s98, s100, 5
	s_and_b32 s18, s98, 0xf80
	s_cmp_lt_u32 s100, 0x800
	s_cbranch_scc1 .Lswz_c3
	s_and_b32 s98, s100, 1
	s_lshl_b32 s98, s98, 8
	s_or_b32 s19, s98, 0x4000
	s_lshl_b32 s98, s100, 6
	s_and_b32 s18, s98, 0xf80
.Lswz_c3:
	s_nop 0
	v_add_u32_e32 v52, s19, v203
	v_add_u32_e32 v48, s18, v203
	v_ashrrev_i32_e32 v53, 31, v52
	v_ashrrev_i32_e32 v49, 31, v48
	v_lshlrev_b64 v[52:53], 11, v[52:53]
	v_lshlrev_b64 v[48:49], 11, v[48:49]
	v_lshl_add_u64 v[182:183], v[172:173], 0, v[52:53]
	v_lshl_add_u64 v[184:185], v[174:175], 0, v[48:49]
	v_mov_b32_e32 v48, 0
	s_mov_b32 s38, 0
	v_lshl_add_u64 v[186:187], v[182:183], 0, s[0:1]
	v_lshl_add_u64 v[188:189], v[182:183], 0, s[2:3]
	v_lshl_add_u64 v[190:191], v[182:183], 0, s[4:5]
	v_lshl_add_u64 v[192:193], v[184:185], 0, s[0:1]
	v_lshl_add_u64 v[194:195], v[182:183], 0, s[6:7]
	v_lshl_add_u64 v[196:197], v[182:183], 0, s[8:9]
	v_lshl_add_u64 v[198:199], v[182:183], 0, s[10:11]
	v_lshl_add_u64 v[200:201], v[184:185], 0, s[6:7]
	v_mov_b32_e32 v49, v48
	v_mov_b32_e32 v50, v48
	v_mov_b32_e32 v51, v48
	v_mov_b32_e32 v52, v48
	v_mov_b32_e32 v53, v48
	v_mov_b32_e32 v54, v48
	v_mov_b32_e32 v55, v48
	v_mov_b32_e32 v56, v48
	v_mov_b32_e32 v57, v48
	v_mov_b32_e32 v58, v48
	v_mov_b32_e32 v59, v48
	v_mov_b32_e32 v60, v48
	v_mov_b32_e32 v61, v48
	v_mov_b32_e32 v62, v48
	v_mov_b32_e32 v63, v48
	v_mov_b32_e32 v64, v48
	v_mov_b32_e32 v65, v48
	v_mov_b32_e32 v66, v48
	v_mov_b32_e32 v67, v48
	v_mov_b32_e32 v68, v48
	v_mov_b32_e32 v69, v48
	v_mov_b32_e32 v70, v48
	v_mov_b32_e32 v71, v48
	v_mov_b32_e32 v72, v48
	v_mov_b32_e32 v73, v48
	v_mov_b32_e32 v74, v48
	v_mov_b32_e32 v75, v48
	v_mov_b32_e32 v76, v48
	v_mov_b32_e32 v77, v48
	v_mov_b32_e32 v78, v48
	v_mov_b32_e32 v79, v48
	v_mov_b32_e32 v80, v48
	v_mov_b32_e32 v81, v48
	v_mov_b32_e32 v82, v48
	v_mov_b32_e32 v83, v48
	v_mov_b32_e32 v84, v48
	v_mov_b32_e32 v85, v48
	v_mov_b32_e32 v86, v48
	v_mov_b32_e32 v87, v48
	v_mov_b32_e32 v88, v48
	v_mov_b32_e32 v89, v48
	v_mov_b32_e32 v90, v48
	v_mov_b32_e32 v91, v48
	v_mov_b32_e32 v92, v48
	v_mov_b32_e32 v93, v48
	v_mov_b32_e32 v94, v48
	v_mov_b32_e32 v95, v48
	v_mov_b32_e32 v96, v48
	v_mov_b32_e32 v97, v48
	v_mov_b32_e32 v98, v48
	v_mov_b32_e32 v99, v48
	v_mov_b32_e32 v100, v48
	v_mov_b32_e32 v101, v48
	v_mov_b32_e32 v102, v48
	v_mov_b32_e32 v103, v48
	v_mov_b32_e32 v104, v48
	v_mov_b32_e32 v105, v48
	v_mov_b32_e32 v106, v48
	v_mov_b32_e32 v107, v48
	v_mov_b32_e32 v108, v48
	v_mov_b32_e32 v109, v48
	v_mov_b32_e32 v110, v48
	v_mov_b32_e32 v111, v48
	s_lshl_b32 s98, s35, 11
	s_add_u32 s98, s76, s98
	s_addc_u32 s99, s77, 0
	s_add_u32 s98, s98, 0x2800000
	s_addc_u32 s99, s99, 0
	s_lshl_b32 s100, s37, 11
	s_add_u32 s100, s76, s100
	s_addc_u32 s101, s77, 0
	s_add_u32 s100, s100, 0xa80000
	s_addc_u32 s101, s101, 0
	v_lshl_add_u32 v180, v203, 11, v176
	v_add_u32_e32 v181, 0x20000, v180
	v_add_u32_e32 v178, 0x40000, v180
	v_add_u32_e32 v179, 0x60000, v180
	s_branch .LBB0_774
.LBB0_774:
	s_waitcnt lgkmcnt(0)
	s_barrier
	ds_read_b128 v[112:115], v206
	ds_read_b128 v[116:119], v206 offset:2048
	ds_read_b128 v[120:123], v206 offset:4096
	ds_read_b128 v[124:127], v206 offset:6144
	ds_read_b128 v[128:131], v207
	ds_read_b128 v[132:135], v207 offset:2048
	ds_read_b128 v[136:139], v207 offset:4096
	ds_read_b128 v[140:143], v207 offset:6144
	s_waitcnt vmcnt(14)
	ds_write_b128 v204, v[0:3] offset:32768
	ds_write_b128 v204, v[4:7] offset:40960
	ds_write_b128 v204, v[8:11] offset:49152
	ds_write_b128 v204, v[16:19] offset:57344
	ds_write_b128 v210, v[28:31]
	ds_write_b128 v210, v[36:39] offset:8192
	s_cmp_gt_u32 s38, 12
	s_mov_b64 s[18:19], -1
	s_cbranch_scc0 .Lmycfe__778
	s_andn2_b64 vcc, exec, s[16:17]
	s_cbranch_vccnz .Lmycfe__777
	global_load_dwordx4 v[4:7], v[186:187], off
	global_load_dwordx4 v[8:11], v[188:189], off
	global_load_dwordx4 v[0:3], v[182:183], off offset:128
	global_load_dwordx4 v[28:31], v[184:185], off offset:128
	global_load_dwordx4 v[16:19], v[190:191], off
	global_load_dwordx4 v[36:39], v[192:193], off

.Lmycfe__778:
	s_andn2_b64 vcc, exec, s[18:19]
	s_cbranch_vccnz .Lmycfe__780
	global_load_dwordx4 v[0:3], v180, s[98:99] offset:384
	global_load_dwordx4 v[4:7], v181, s[98:99] offset:384
	global_load_dwordx4 v[8:11], v178, s[98:99] offset:384
	global_load_dwordx4 v[16:19], v179, s[98:99] offset:384
	global_load_dwordx4 v[28:31], v180, s[100:101] offset:384
	global_load_dwordx4 v[36:39], v181, s[100:101] offset:384

.Lmycso__785:
	s_andn2_b64 vcc, exec, s[20:21]
	s_cbranch_vccnz .Lmyc_ocont
	global_load_dwordx4 v[12:15], v180, s[98:99] offset:512
	global_load_dwordx4 v[20:23], v181, s[98:99] offset:512
	global_load_dwordx4 v[32:35], v178, s[98:99] offset:512
	global_load_dwordx4 v[24:27], v179, s[98:99] offset:512
	global_load_dwordx4 v[44:47], v180, s[100:101] offset:512
	global_load_dwordx4 v[40:43], v181, s[100:101] offset:512
.Lmyc_ocont:
	v_mfma_f32_16x16x32_bf16 v[76:79], v[160:163], v[152:155], v[76:79]
	v_mfma_f32_16x16x32_bf16 v[72:75], v[164:167], v[152:155], v[72:75]
	v_mfma_f32_16x16x32_bf16 v[68:71], v[216:219], v[152:155], v[68:71]
	v_mfma_f32_16x16x32_bf16 v[64:67], v[228:231], v[152:155], v[64:67]
	v_mfma_f32_16x16x32_bf16 v[60:63], v[160:163], v[156:159], v[60:63]
	v_mfma_f32_16x16x32_bf16 v[56:59], v[164:167], v[156:159], v[56:59]
	v_mfma_f32_16x16x32_bf16 v[52:55], v[216:219], v[156:159], v[52:55]
	v_mfma_f32_16x16x32_bf16 v[48:51], v[228:231], v[156:159], v[48:51]
	s_waitcnt lgkmcnt(0)
	v_mfma_f32_16x16x32_bf16 v[108:111], v[128:131], v[112:115], v[108:111]
	ds_read_b128 v[144:147], v208 offset:32768
	v_mfma_f32_16x16x32_bf16 v[104:107], v[132:135], v[112:115], v[104:107]
	ds_read_b128 v[148:151], v208 offset:34816
	v_mfma_f32_16x16x32_bf16 v[100:103], v[136:139], v[112:115], v[100:103]
	ds_read_b128 v[152:155], v208 offset:36864
	v_mfma_f32_16x16x32_bf16 v[96:99], v[140:143], v[112:115], v[96:99]
	ds_read_b128 v[156:159], v208 offset:38912
	v_mfma_f32_16x16x32_bf16 v[92:95], v[128:131], v[116:119], v[92:95]
	ds_read_b128 v[160:163], v212
	v_mfma_f32_16x16x32_bf16 v[88:91], v[132:135], v[116:119], v[88:91]
	ds_read_b128 v[164:167], v212 offset:2048
	v_mfma_f32_16x16x32_bf16 v[84:87], v[136:139], v[116:119], v[84:87]
	ds_read_b128 v[216:219], v212 offset:4096
	v_mfma_f32_16x16x32_bf16 v[80:83], v[140:143], v[116:119], v[80:83]
	ds_read_b128 v[228:231], v212 offset:6144
	v_mfma_f32_16x16x32_bf16 v[76:79], v[128:131], v[120:123], v[76:79]
	v_mfma_f32_16x16x32_bf16 v[72:75], v[132:135], v[120:123], v[72:75]
	v_mfma_f32_16x16x32_bf16 v[68:71], v[136:139], v[120:123], v[68:71]
	v_mfma_f32_16x16x32_bf16 v[64:67], v[140:143], v[120:123], v[64:67]
	v_mfma_f32_16x16x32_bf16 v[60:63], v[128:131], v[124:127], v[60:63]
	v_mfma_f32_16x16x32_bf16 v[56:59], v[132:135], v[124:127], v[56:59]
	v_mfma_f32_16x16x32_bf16 v[52:55], v[136:139], v[124:127], v[52:55]
	v_mfma_f32_16x16x32_bf16 v[48:51], v[140:143], v[124:127], v[48:51]
	s_add_i32 s38, s38, 2
	s_add_u32 s100, s100, 0x100
	s_addc_u32 s101, s101, 0
	s_add_u32 s98, s98, 0x100
	s_addc_u32 s99, s99, 0
	s_branch .Lmyc_even
.Lmyc_oddlast:
	v_mfma_f32_16x16x32_bf16 v[108:111], v[160:163], v[144:147], v[108:111]
	v_mfma_f32_16x16x32_bf16 v[104:107], v[164:167], v[144:147], v[104:107]
	v_mfma_f32_16x16x32_bf16 v[100:103], v[216:219], v[144:147], v[100:103]
	v_mfma_f32_16x16x32_bf16 v[96:99], v[228:231], v[144:147], v[96:99]
	v_mfma_f32_16x16x32_bf16 v[92:95], v[160:163], v[148:151], v[92:95]
	v_mfma_f32_16x16x32_bf16 v[88:91], v[164:167], v[148:151], v[88:91]
	v_mfma_f32_16x16x32_bf16 v[84:87], v[216:219], v[148:151], v[84:87]
	v_mfma_f32_16x16x32_bf16 v[80:83], v[228:231], v[148:151], v[80:83]
	v_mfma_f32_16x16x32_bf16 v[76:79], v[160:163], v[152:155], v[76:79]
	v_mfma_f32_16x16x32_bf16 v[72:75], v[164:167], v[152:155], v[72:75]
	v_mfma_f32_16x16x32_bf16 v[68:71], v[216:219], v[152:155], v[68:71]
	v_mfma_f32_16x16x32_bf16 v[64:67], v[228:231], v[152:155], v[64:67]
	v_mfma_f32_16x16x32_bf16 v[60:63], v[160:163], v[156:159], v[60:63]
	v_mfma_f32_16x16x32_bf16 v[56:59], v[164:167], v[156:159], v[56:59]
	v_mfma_f32_16x16x32_bf16 v[52:55], v[216:219], v[156:159], v[52:55]
	v_mfma_f32_16x16x32_bf16 v[48:51], v[228:231], v[156:159], v[48:51]
	s_waitcnt lgkmcnt(0)
	v_mfma_f32_16x16x32_bf16 v[108:111], v[128:131], v[112:115], v[108:111]
	ds_read_b128 v[144:147], v208 offset:32768
	v_mfma_f32_16x16x32_bf16 v[104:107], v[132:135], v[112:115], v[104:107]
	ds_read_b128 v[148:151], v208 offset:34816
	v_mfma_f32_16x16x32_bf16 v[100:103], v[136:139], v[112:115], v[100:103]
	ds_read_b128 v[152:155], v208 offset:36864
	v_mfma_f32_16x16x32_bf16 v[96:99], v[140:143], v[112:115], v[96:99]
	ds_read_b128 v[156:159], v208 offset:38912
	v_mfma_f32_16x16x32_bf16 v[92:95], v[128:131], v[116:119], v[92:95]
	ds_read_b128 v[160:163], v212
	v_mfma_f32_16x16x32_bf16 v[88:91], v[132:135], v[116:119], v[88:91]
	ds_read_b128 v[164:167], v212 offset:2048
	v_mfma_f32_16x16x32_bf16 v[84:87], v[136:139], v[116:119], v[84:87]
	ds_read_b128 v[216:219], v212 offset:4096
	v_mfma_f32_16x16x32_bf16 v[80:83], v[140:143], v[116:119], v[80:83]
	ds_read_b128 v[228:231], v212 offset:6144
	v_mfma_f32_16x16x32_bf16 v[76:79], v[128:131], v[120:123], v[76:79]
	v_mfma_f32_16x16x32_bf16 v[72:75], v[132:135], v[120:123], v[72:75]
	v_mfma_f32_16x16x32_bf16 v[68:71], v[136:139], v[120:123], v[68:71]
	v_mfma_f32_16x16x32_bf16 v[64:67], v[140:143], v[120:123], v[64:67]
	v_mfma_f32_16x16x32_bf16 v[60:63], v[128:131], v[124:127], v[60:63]
	v_mfma_f32_16x16x32_bf16 v[56:59], v[132:135], v[124:127], v[56:59]
	v_mfma_f32_16x16x32_bf16 v[52:55], v[136:139], v[124:127], v[52:55]
	v_mfma_f32_16x16x32_bf16 v[48:51], v[140:143], v[124:127], v[48:51]
	s_add_i32 s38, s38, 2
	s_add_u32 s100, s100, 0x100
	s_addc_u32 s101, s101, 0
	s_add_u32 s98, s98, 0x100
	s_addc_u32 s99, s99, 0
	s_waitcnt lgkmcnt(0)
	v_mfma_f32_16x16x32_bf16 v[108:111], v[160:163], v[144:147], v[108:111]
	v_mfma_f32_16x16x32_bf16 v[104:107], v[164:167], v[144:147], v[104:107]
	v_mfma_f32_16x16x32_bf16 v[100:103], v[216:219], v[144:147], v[100:103]
	v_mfma_f32_16x16x32_bf16 v[96:99], v[228:231], v[144:147], v[96:99]
	v_mfma_f32_16x16x32_bf16 v[92:95], v[160:163], v[148:151], v[92:95]
	v_mfma_f32_16x16x32_bf16 v[88:91], v[164:167], v[148:151], v[88:91]
	v_mfma_f32_16x16x32_bf16 v[84:87], v[216:219], v[148:151], v[84:87]
	v_mfma_f32_16x16x32_bf16 v[80:83], v[228:231], v[148:151], v[80:83]
	v_mfma_f32_16x16x32_bf16 v[76:79], v[160:163], v[152:155], v[76:79]
	v_mfma_f32_16x16x32_bf16 v[72:75], v[164:167], v[152:155], v[72:75]
	v_mfma_f32_16x16x32_bf16 v[68:71], v[216:219], v[152:155], v[68:71]
	v_mfma_f32_16x16x32_bf16 v[64:67], v[228:231], v[152:155], v[64:67]
	v_mfma_f32_16x16x32_bf16 v[60:63], v[160:163], v[156:159], v[60:63]
	v_mfma_f32_16x16x32_bf16 v[56:59], v[164:167], v[156:159], v[56:59]
	v_mfma_f32_16x16x32_bf16 v[52:55], v[216:219], v[156:159], v[52:55]
	v_mfma_f32_16x16x32_bf16 v[48:51], v[228:231], v[156:159], v[48:51]
	s_and_b64 vcc, exec, s[18:19]
	s_nop 7
	s_branch .LBB0_769

.LBB0_1038:
	s_barrier
	s_waitcnt vmcnt(0)
	ds_write_b128 v222, v[38:41]
	s_waitcnt vmcnt(0)
	ds_write_b128 v222, v[46:49] offset:8192
	ds_write_b128 v222, v[34:37] offset:16384
	ds_write_b128 v222, v[42:45] offset:24576
	ds_write_b128 v223, v[22:25]
	ds_write_b128 v223, v[30:33] offset:8192
	v_add_co_u32_e32 v22, vcc, s79, v52
	s_mov_b32 s0, s8
	s_nop 0
	v_addc_co_u32_e32 v23, vcc, 0, v53, vcc
	v_add_co_u32_e32 v34, vcc, 0x60000, v50
	global_load_dwordx4 v[30:33], v[22:23], off offset:256
	s_nop 0
	global_load_dwordx4 v[22:25], v[52:53], off offset:256
	v_addc_co_u32_e32 v35, vcc, 0, v51, vcc
	global_load_dwordx4 v[42:45], v[34:35], off offset:256
	v_add_co_u32_e32 v34, vcc, 0x40000, v50
	v_add_u32_e32 v54, s0, v221
	s_nop 0
	v_addc_co_u32_e32 v35, vcc, 0, v51, vcc
	v_add_co_u32_e32 v38, vcc, 0x20000, v50
	global_load_dwordx4 v[34:37], v[34:35], off offset:256
	s_nop 0
	v_addc_co_u32_e32 v39, vcc, 0, v51, vcc
	global_load_dwordx4 v[46:49], v[38:39], off offset:256
	s_nop 0
	global_load_dwordx4 v[38:41], v[50:51], off offset:256
	s_mov_b32 s0, s9
	s_add_i32 s12, s12, s51
	s_cmp_ge_i32 s12, s15
	v_ashrrev_i32_e32 v55, 31, v54
	s_cselect_b64 s[6:7], -1, 0
	s_add_i32 s4, s12, s14
	v_lshlrev_b64 v[54:55], 11, v[54:55]
	s_cmp_lt_i32 s12, s15
	s_nop 0
	v_add_u32_e32 v54, s0, v221
	s_cselect_b64 s[0:1], -1, 0
	s_and_b64 s[2:3], s[0:1], exec
	s_cselect_b32 s2, s4, 0
	v_ashrrev_i32_e32 v55, 31, v54
	s_mov_b32 s100, s2
	s_lshr_b32 s98, s100, 8
	s_lshl_b32 s98, s98, 10
	s_and_b32 s99, s100, 3
	s_lshl_b32 s99, s99, 8
	s_or_b32 s3, s98, s99
	s_lshl_b32 s98, s100, 5
	s_and_b32 s2, s98, 0x1f80
	s_cmp_lt_u32 s100, 0x800
	s_cbranch_scc1 .Lswz_d3
	s_mov_b32 s3, 0x2000
	s_lshl_b32 s98, s100, 7
	s_and_b32 s2, s98, 0x1f80
.Lswz_d3:
	v_lshlrev_b64 v[54:55], 11, v[54:55]
	s_nop 0
	v_add_u32_e32 v54, s3, v221
	v_ashrrev_i32_e32 v55, 31, v54
	v_lshlrev_b64 v[54:55], 11, v[54:55]
	v_add_u32_e32 v56, s2, v221
	v_lshl_add_u64 v[180:181], v[168:169], 0, v[54:55]
	s_mov_b64 s[2:3], 0x40080
	v_ashrrev_i32_e32 v57, 31, v56
	v_lshl_add_u64 v[186:187], v[180:181], 0, s[2:3]
	s_mov_b64 s[2:3], 0x60080
	v_lshlrev_b64 v[56:57], 11, v[56:57]
	v_lshl_add_u64 v[188:189], v[180:181], 0, s[2:3]
	s_mov_b64 s[2:3], 0x40000
	v_lshl_add_u64 v[182:183], v[172:173], 0, v[56:57]
	s_mov_b64 s[4:5], 0x20000
	v_lshl_add_u64 v[194:195], v[180:181], 0, s[2:3]
	s_mov_b64 s[2:3], 0x60000
	v_mov_b32_e32 v50, 0
	s_mov_b32 s13, 0
	v_lshl_add_u64 v[184:185], v[180:181], 0, s[62:63]
	v_lshl_add_u64 v[190:191], v[182:183], 0, s[62:63]
	v_lshl_add_u64 v[192:193], v[180:181], 0, s[4:5]
	v_lshl_add_u64 v[196:197], v[180:181], 0, s[2:3]
	s_mov_b64 s[64:65], 0x20000
	v_lshl_add_u64 v[198:199], v[182:183], 0, s[4:5]
	v_mov_b32_e32 v51, v50
	v_mov_b32_e32 v52, v50
	v_mov_b32_e32 v53, v50
	v_mov_b32_e32 v54, v50
	v_mov_b32_e32 v55, v50
	v_mov_b32_e32 v56, v50
	v_mov_b32_e32 v57, v50
	v_mov_b32_e32 v82, v50
	v_mov_b32_e32 v83, v50
	v_mov_b32_e32 v84, v50
	v_mov_b32_e32 v85, v50
	v_mov_b32_e32 v86, v50
	v_mov_b32_e32 v87, v50
	v_mov_b32_e32 v88, v50
	v_mov_b32_e32 v89, v50
	v_mov_b32_e32 v58, v50
	v_mov_b32_e32 v59, v50
	v_mov_b32_e32 v60, v50
	v_mov_b32_e32 v61, v50
	v_mov_b32_e32 v62, v50
	v_mov_b32_e32 v63, v50
	v_mov_b32_e32 v64, v50
	v_mov_b32_e32 v65, v50
	v_mov_b32_e32 v90, v50
	v_mov_b32_e32 v91, v50
	v_mov_b32_e32 v92, v50
	v_mov_b32_e32 v93, v50
	v_mov_b32_e32 v94, v50
	v_mov_b32_e32 v95, v50
	v_mov_b32_e32 v96, v50
	v_mov_b32_e32 v97, v50
	v_mov_b32_e32 v66, v50
	v_mov_b32_e32 v67, v50
	v_mov_b32_e32 v68, v50
	v_mov_b32_e32 v69, v50
	v_mov_b32_e32 v70, v50
	v_mov_b32_e32 v71, v50
	v_mov_b32_e32 v72, v50
	v_mov_b32_e32 v73, v50
	v_mov_b32_e32 v98, v50
	v_mov_b32_e32 v99, v50
	v_mov_b32_e32 v100, v50
	v_mov_b32_e32 v101, v50
	v_mov_b32_e32 v102, v50
	v_mov_b32_e32 v103, v50
	v_mov_b32_e32 v104, v50
	v_mov_b32_e32 v105, v50
	v_mov_b32_e32 v74, v50
	v_mov_b32_e32 v75, v50
	v_mov_b32_e32 v76, v50
	v_mov_b32_e32 v77, v50
	v_mov_b32_e32 v78, v50
	v_mov_b32_e32 v79, v50
	v_mov_b32_e32 v80, v50
	v_mov_b32_e32 v81, v50
	v_mov_b32_e32 v106, v50
	v_mov_b32_e32 v107, v50
	v_mov_b32_e32 v108, v50
	v_mov_b32_e32 v109, v50
	v_mov_b32_e32 v110, v50
	v_mov_b32_e32 v111, v50
	v_mov_b32_e32 v112, v50
	v_mov_b32_e32 v113, v50
	s_lshl_b32 s98, s9, 11
	s_add_u32 s98, s76, s98
	s_addc_u32 s99, s77, 0
	s_add_u32 s98, s98, 0x2800000
	s_addc_u32 s99, s99, 0
	s_lshl_b32 s100, s8, 11
	s_add_u32 s100, s76, s100
	s_addc_u32 s101, s77, 0
	s_add_u32 s100, s100, 0x400000
	s_addc_u32 s101, s101, 0
	v_lshl_add_u32 v178, v221, 11, v174
	v_add_u32_e32 v179, 0x20000, v178
	v_add_u32_e32 v176, 0x40000, v178
	v_add_u32_e32 v177, 0x60000, v178
	s_branch .LBB0_1040

.Lmydfe__1044:
	s_andn2_b64 vcc, exec, s[2:3]
	s_cbranch_vccnz .Lmydfe__1046
	global_load_dwordx4 v[2:5], v178, s[98:99] offset:384
	global_load_dwordx4 v[6:9], v179, s[98:99] offset:384
	global_load_dwordx4 v[10:13], v176, s[98:99] offset:384
	global_load_dwordx4 v[14:17], v177, s[98:99] offset:384
	global_load_dwordx4 v[18:21], v178, s[100:101] offset:384
	global_load_dwordx4 v[26:29], v179, s[100:101] offset:384

.Lmydso__1051:
	s_andn2_b64 vcc, exec, s[4:5]
	s_cbranch_vccnz .Lmyd_ocont
	global_load_dwordx4 v[38:41], v178, s[98:99] offset:512
	global_load_dwordx4 v[46:49], v179, s[98:99] offset:512
	global_load_dwordx4 v[34:37], v176, s[98:99] offset:512
	global_load_dwordx4 v[42:45], v177, s[98:99] offset:512
	global_load_dwordx4 v[22:25], v178, s[100:101] offset:512
	global_load_dwordx4 v[30:33], v179, s[100:101] offset:512
.Lmyd_ocont:
	v_mfma_f32_16x16x32_bf16 v[94:97], v[154:157], v[162:165], v[94:97]
	v_mfma_f32_16x16x32_bf16 v[90:93], v[154:157], v[234:237], v[90:93]
	v_mfma_f32_16x16x32_bf16 v[62:65], v[154:157], v[238:241], v[62:65]
	v_mfma_f32_16x16x32_bf16 v[58:61], v[154:157], v[242:245], v[58:61]
	v_mfma_f32_16x16x32_bf16 v[86:89], v[158:161], v[162:165], v[86:89]
	v_mfma_f32_16x16x32_bf16 v[82:85], v[158:161], v[234:237], v[82:85]
	v_mfma_f32_16x16x32_bf16 v[54:57], v[158:161], v[238:241], v[54:57]
	v_mfma_f32_16x16x32_bf16 v[50:53], v[158:161], v[242:245], v[50:53]
	s_waitcnt lgkmcnt(0)
	v_mfma_f32_16x16x32_bf16 v[110:113], v[114:117], v[130:133], v[110:113]
	ds_read_b128 v[146:149], v226 offset:32768
	v_mfma_f32_16x16x32_bf16 v[106:109], v[114:117], v[134:137], v[106:109]
	ds_read_b128 v[150:153], v226 offset:34816
	v_mfma_f32_16x16x32_bf16 v[78:81], v[114:117], v[138:141], v[78:81]
	ds_read_b128 v[154:157], v226 offset:36864
	v_mfma_f32_16x16x32_bf16 v[74:77], v[114:117], v[142:145], v[74:77]
	ds_read_b128 v[158:161], v226 offset:38912
	v_mfma_f32_16x16x32_bf16 v[102:105], v[118:121], v[130:133], v[102:105]
	ds_read_b128 v[162:165], v230
	v_mfma_f32_16x16x32_bf16 v[98:101], v[118:121], v[134:137], v[98:101]
	ds_read_b128 v[234:237], v230 offset:2048
	v_mfma_f32_16x16x32_bf16 v[70:73], v[118:121], v[138:141], v[70:73]
	ds_read_b128 v[238:241], v230 offset:4096
	v_mfma_f32_16x16x32_bf16 v[66:69], v[118:121], v[142:145], v[66:69]
	ds_read_b128 v[242:245], v230 offset:6144
	v_mfma_f32_16x16x32_bf16 v[94:97], v[122:125], v[130:133], v[94:97]
	v_mfma_f32_16x16x32_bf16 v[90:93], v[122:125], v[134:137], v[90:93]
	v_mfma_f32_16x16x32_bf16 v[62:65], v[122:125], v[138:141], v[62:65]
	v_mfma_f32_16x16x32_bf16 v[58:61], v[122:125], v[142:145], v[58:61]
	v_mfma_f32_16x16x32_bf16 v[86:89], v[126:129], v[130:133], v[86:89]
	v_mfma_f32_16x16x32_bf16 v[82:85], v[126:129], v[134:137], v[82:85]
	v_mfma_f32_16x16x32_bf16 v[54:57], v[126:129], v[138:141], v[54:57]
	v_mfma_f32_16x16x32_bf16 v[50:53], v[126:129], v[142:145], v[50:53]
	s_add_i32 s13, s13, 2
	s_add_u32 s100, s100, 0x100
	s_addc_u32 s101, s101, 0
	s_add_u32 s98, s98, 0x100
	s_addc_u32 s99, s99, 0
	s_branch .Lmyd_even
.Lmyd_oddlast:
	v_mfma_f32_16x16x32_bf16 v[110:113], v[146:149], v[162:165], v[110:113]
	v_mfma_f32_16x16x32_bf16 v[106:109], v[146:149], v[234:237], v[106:109]
	v_mfma_f32_16x16x32_bf16 v[78:81], v[146:149], v[238:241], v[78:81]
	v_mfma_f32_16x16x32_bf16 v[74:77], v[146:149], v[242:245], v[74:77]
	v_mfma_f32_16x16x32_bf16 v[102:105], v[150:153], v[162:165], v[102:105]
	v_mfma_f32_16x16x32_bf16 v[98:101], v[150:153], v[234:237], v[98:101]
	v_mfma_f32_16x16x32_bf16 v[70:73], v[150:153], v[238:241], v[70:73]
	v_mfma_f32_16x16x32_bf16 v[66:69], v[150:153], v[242:245], v[66:69]
	v_mfma_f32_16x16x32_bf16 v[94:97], v[154:157], v[162:165], v[94:97]
	v_mfma_f32_16x16x32_bf16 v[90:93], v[154:157], v[234:237], v[90:93]
	v_mfma_f32_16x16x32_bf16 v[62:65], v[154:157], v[238:241], v[62:65]
	v_mfma_f32_16x16x32_bf16 v[58:61], v[154:157], v[242:245], v[58:61]
	v_mfma_f32_16x16x32_bf16 v[86:89], v[158:161], v[162:165], v[86:89]
	v_mfma_f32_16x16x32_bf16 v[82:85], v[158:161], v[234:237], v[82:85]
	v_mfma_f32_16x16x32_bf16 v[54:57], v[158:161], v[238:241], v[54:57]
	v_mfma_f32_16x16x32_bf16 v[50:53], v[158:161], v[242:245], v[50:53]
	s_waitcnt lgkmcnt(0)
	v_mfma_f32_16x16x32_bf16 v[110:113], v[114:117], v[130:133], v[110:113]
	ds_read_b128 v[146:149], v226 offset:32768
	v_mfma_f32_16x16x32_bf16 v[106:109], v[114:117], v[134:137], v[106:109]
	ds_read_b128 v[150:153], v226 offset:34816
	v_mfma_f32_16x16x32_bf16 v[78:81], v[114:117], v[138:141], v[78:81]
	ds_read_b128 v[154:157], v226 offset:36864
	v_mfma_f32_16x16x32_bf16 v[74:77], v[114:117], v[142:145], v[74:77]
	ds_read_b128 v[158:161], v226 offset:38912
	v_mfma_f32_16x16x32_bf16 v[102:105], v[118:121], v[130:133], v[102:105]
	ds_read_b128 v[162:165], v230
	v_mfma_f32_16x16x32_bf16 v[98:101], v[118:121], v[134:137], v[98:101]
	ds_read_b128 v[234:237], v230 offset:2048
	v_mfma_f32_16x16x32_bf16 v[70:73], v[118:121], v[138:141], v[70:73]
	ds_read_b128 v[238:241], v230 offset:4096
	v_mfma_f32_16x16x32_bf16 v[66:69], v[118:121], v[142:145], v[66:69]
	ds_read_b128 v[242:245], v230 offset:6144
	v_mfma_f32_16x16x32_bf16 v[94:97], v[122:125], v[130:133], v[94:97]
	v_mfma_f32_16x16x32_bf16 v[90:93], v[122:125], v[134:137], v[90:93]
	v_mfma_f32_16x16x32_bf16 v[62:65], v[122:125], v[138:141], v[62:65]
	v_mfma_f32_16x16x32_bf16 v[58:61], v[122:125], v[142:145], v[58:61]
	v_mfma_f32_16x16x32_bf16 v[86:89], v[126:129], v[130:133], v[86:89]
	v_mfma_f32_16x16x32_bf16 v[82:85], v[126:129], v[134:137], v[82:85]
	v_mfma_f32_16x16x32_bf16 v[54:57], v[126:129], v[138:141], v[54:57]
	v_mfma_f32_16x16x32_bf16 v[50:53], v[126:129], v[142:145], v[50:53]
	s_add_i32 s13, s13, 2
	s_add_u32 s100, s100, 0x100
	s_addc_u32 s101, s101, 0
	s_add_u32 s98, s98, 0x100
	s_addc_u32 s99, s99, 0
	s_waitcnt lgkmcnt(0)
	v_mfma_f32_16x16x32_bf16 v[110:113], v[146:149], v[162:165], v[110:113]
	v_mfma_f32_16x16x32_bf16 v[106:109], v[146:149], v[234:237], v[106:109]
	v_mfma_f32_16x16x32_bf16 v[78:81], v[146:149], v[238:241], v[78:81]
	v_mfma_f32_16x16x32_bf16 v[74:77], v[146:149], v[242:245], v[74:77]
	v_mfma_f32_16x16x32_bf16 v[102:105], v[150:153], v[162:165], v[102:105]
	v_mfma_f32_16x16x32_bf16 v[98:101], v[150:153], v[234:237], v[98:101]
	v_mfma_f32_16x16x32_bf16 v[70:73], v[150:153], v[238:241], v[70:73]
	v_mfma_f32_16x16x32_bf16 v[66:69], v[150:153], v[242:245], v[66:69]
	v_mfma_f32_16x16x32_bf16 v[94:97], v[154:157], v[162:165], v[94:97]
	v_mfma_f32_16x16x32_bf16 v[90:93], v[154:157], v[234:237], v[90:93]
	v_mfma_f32_16x16x32_bf16 v[62:65], v[154:157], v[238:241], v[62:65]
	v_mfma_f32_16x16x32_bf16 v[58:61], v[154:157], v[242:245], v[58:61]
	v_mfma_f32_16x16x32_bf16 v[86:89], v[158:161], v[162:165], v[86:89]
	v_mfma_f32_16x16x32_bf16 v[82:85], v[158:161], v[234:237], v[82:85]
	v_mfma_f32_16x16x32_bf16 v[54:57], v[158:161], v[238:241], v[54:57]
	v_mfma_f32_16x16x32_bf16 v[50:53], v[158:161], v[242:245], v[50:53]
	s_and_b64 vcc, exec, s[2:3]
	s_nop 7
	s_branch .LBB0_1053

.LBB0_1362:
	s_and_b32 s0, s9, 0x380
	v_add_u32_e32 v54, s0, v221
	v_ashrrev_i32_e32 v55, 31, v54
	s_and_b32 s0, s8, 0x7fffff00
	s_add_i32 s10, s10, s51
	v_lshlrev_b64 v[54:55], 12, v[54:55]
	s_cmp_gt_u32 s10, 31
	s_nop 0
	v_add_u32_e32 v54, s0, v221
	s_cselect_b64 s[0:1], -1, 0
	s_add_i32 s6, s10, s20
	s_cmp_lt_u32 s10, 32
	s_cselect_b64 s[2:3], -1, 0
	s_and_b64 s[4:5], s[2:3], exec
	s_cselect_b32 s4, s6, 0
	s_lshl_b32 s5, s4, 5
	s_lshl_b32 s4, s4, 7
	s_and_b32 s4, s4, 0x380
	v_add_u32_e32 v56, s4, v221
	s_mov_b32 s4, 0x40000
	s_barrier
	s_waitcnt vmcnt(11)
	ds_write_b128 v222, v[2:5]
	s_waitcnt vmcnt(4)
	ds_write_b128 v222, v[14:17] offset:8192
	s_waitcnt vmcnt(0)
	ds_write_b128 v222, v[30:33] offset:16384
	ds_write_b128 v222, v[38:41] offset:24576
	ds_write_b128 v223, v[42:45]
	ds_write_b128 v223, v[46:49] offset:8192
	v_add_co_u32_e32 v14, vcc, s4, v52
	global_load_dwordx4 v[2:5], v[52:53], off offset:256
	s_nop 0
	v_addc_co_u32_e32 v15, vcc, 0, v53, vcc
	v_add_co_u32_e32 v30, vcc, 0x80000, v52
	global_load_dwordx4 v[14:17], v[14:15], off offset:256
	s_nop 0
	v_addc_co_u32_e32 v31, vcc, 0, v53, vcc
	v_add_co_u32_e32 v38, vcc, 0xc0000, v52
	global_load_dwordx4 v[30:33], v[30:31], off offset:256
	s_nop 0
	v_addc_co_u32_e32 v39, vcc, 0, v53, vcc
	v_add_co_u32_e32 v46, vcc, 0x40000, v50
	global_load_dwordx4 v[38:41], v[38:39], off offset:256
	s_nop 0
	global_load_dwordx4 v[42:45], v[50:51], off offset:256
	v_addc_co_u32_e32 v47, vcc, 0, v51, vcc
	global_load_dwordx4 v[46:49], v[46:47], off offset:256
	v_ashrrev_i32_e32 v55, 31, v54
	v_lshlrev_b64 v[54:55], 12, v[54:55]
	s_and_b32 s5, s5, 0x7fffff00
	s_nop 0
	v_add_u32_e32 v54, s5, v221
	v_ashrrev_i32_e32 v55, 31, v54
	v_lshlrev_b64 v[54:55], 12, v[54:55]
	v_ashrrev_i32_e32 v57, 31, v56
	v_lshl_add_u64 v[182:183], v[172:173], 0, v[54:55]
	s_mov_b64 s[4:5], 0x80080
	v_lshlrev_b64 v[54:55], 12, v[56:57]
	v_lshl_add_u64 v[188:189], v[182:183], 0, s[4:5]
	s_mov_b64 s[4:5], 0xc0080
	v_lshl_add_u64 v[184:185], v[174:175], 0, v[54:55]
	s_mov_b64 s[6:7], 0x40080
	v_lshl_add_u64 v[190:191], v[182:183], 0, s[4:5]
	s_mov_b64 s[4:5], 0x80000
	v_lshl_add_u64 v[186:187], v[182:183], 0, s[6:7]
	v_lshl_add_u64 v[192:193], v[184:185], 0, s[6:7]
	s_mov_b64 s[6:7], 0x40000
	v_lshl_add_u64 v[196:197], v[182:183], 0, s[4:5]
	s_mov_b64 s[4:5], 0xc0000
	v_mov_b32_e32 v50, 0
	s_mov_b32 s13, 0
	v_lshl_add_u64 v[194:195], v[182:183], 0, s[6:7]
	v_lshl_add_u64 v[198:199], v[182:183], 0, s[4:5]
	v_lshl_add_u64 v[200:201], v[184:185], 0, s[6:7]
	v_mov_b32_e32 v51, v50
	v_mov_b32_e32 v52, v50
	v_mov_b32_e32 v53, v50
	v_mov_b32_e32 v54, v50
	v_mov_b32_e32 v55, v50
	v_mov_b32_e32 v56, v50
	v_mov_b32_e32 v57, v50
	v_mov_b32_e32 v58, v50
	v_mov_b32_e32 v59, v50
	v_mov_b32_e32 v60, v50
	v_mov_b32_e32 v61, v50
	v_mov_b32_e32 v62, v50
	v_mov_b32_e32 v63, v50
	v_mov_b32_e32 v64, v50
	v_mov_b32_e32 v65, v50
	v_mov_b32_e32 v66, v50
	v_mov_b32_e32 v67, v50
	v_mov_b32_e32 v68, v50
	v_mov_b32_e32 v69, v50
	v_mov_b32_e32 v70, v50
	v_mov_b32_e32 v71, v50
	v_mov_b32_e32 v72, v50
	v_mov_b32_e32 v73, v50
	v_mov_b32_e32 v74, v50
	v_mov_b32_e32 v75, v50
	v_mov_b32_e32 v76, v50
	v_mov_b32_e32 v77, v50
	v_mov_b32_e32 v78, v50
	v_mov_b32_e32 v79, v50
	v_mov_b32_e32 v80, v50
	v_mov_b32_e32 v81, v50
	v_mov_b32_e32 v82, v50
	v_mov_b32_e32 v83, v50
	v_mov_b32_e32 v84, v50
	v_mov_b32_e32 v85, v50
	v_mov_b32_e32 v86, v50
	v_mov_b32_e32 v87, v50
	v_mov_b32_e32 v88, v50
	v_mov_b32_e32 v89, v50
	v_mov_b32_e32 v90, v50
	v_mov_b32_e32 v91, v50
	v_mov_b32_e32 v92, v50
	v_mov_b32_e32 v93, v50
	v_mov_b32_e32 v94, v50
	v_mov_b32_e32 v95, v50
	v_mov_b32_e32 v96, v50
	v_mov_b32_e32 v97, v50
	v_mov_b32_e32 v98, v50
	v_mov_b32_e32 v99, v50
	v_mov_b32_e32 v100, v50
	v_mov_b32_e32 v101, v50
	v_mov_b32_e32 v102, v50
	v_mov_b32_e32 v103, v50
	v_mov_b32_e32 v104, v50
	v_mov_b32_e32 v105, v50
	v_mov_b32_e32 v106, v50
	v_mov_b32_e32 v107, v50
	v_mov_b32_e32 v108, v50
	v_mov_b32_e32 v109, v50
	v_mov_b32_e32 v110, v50
	v_mov_b32_e32 v111, v50
	v_mov_b32_e32 v112, v50
	v_mov_b32_e32 v113, v50
	s_lshl_b32 s98, s11, 12
	s_add_u32 s98, s76, s98
	s_addc_u32 s99, s77, 0
	s_add_u32 s98, s98, 0xab00000
	s_addc_u32 s99, s99, 0
	s_lshl_b32 s100, s12, 12
	s_add_u32 s100, s76, s100
	s_addc_u32 s101, s77, 0
	s_add_u32 s100, s100, 0x1400000
	s_addc_u32 s101, s101, 0
	v_lshl_add_u32 v180, v221, 12, v176
	v_add_u32_e32 v181, 0x40000, v180
	v_add_u32_e32 v178, 0x80000, v180
	v_add_u32_e32 v179, 0xc0000, v180
	s_branch .LBB0_1364

.Lmyefe__1368:
	s_andn2_b64 vcc, exec, s[4:5]
	s_cbranch_vccnz .Lmyefe__1370
	global_load_dwordx4 v[6:9], v180, s[98:99] offset:384
	global_load_dwordx4 v[10:13], v181, s[98:99] offset:384
	global_load_dwordx4 v[18:21], v178, s[98:99] offset:384
	global_load_dwordx4 v[22:25], v179, s[98:99] offset:384
	global_load_dwordx4 v[26:29], v180, s[100:101] offset:384
	global_load_dwordx4 v[34:37], v181, s[100:101] offset:384

.Lmyeso__1375:
	s_andn2_b64 vcc, exec, s[6:7]
	s_cbranch_vccnz .Lmye_ocont
	global_load_dwordx4 v[2:5], v180, s[98:99] offset:512
	global_load_dwordx4 v[14:17], v181, s[98:99] offset:512
	global_load_dwordx4 v[30:33], v178, s[98:99] offset:512
	global_load_dwordx4 v[38:41], v179, s[98:99] offset:512
	global_load_dwordx4 v[42:45], v180, s[100:101] offset:512
	global_load_dwordx4 v[46:49], v181, s[100:101] offset:512
.Lmye_ocont:
	v_mfma_f32_16x16x32_bf16 v[78:81], v[154:157], v[162:165], v[78:81]
	v_mfma_f32_16x16x32_bf16 v[74:77], v[154:157], v[166:169], v[74:77]
	v_mfma_f32_16x16x32_bf16 v[70:73], v[154:157], v[234:237], v[70:73]
	v_mfma_f32_16x16x32_bf16 v[66:69], v[154:157], v[238:241], v[66:69]
	v_mfma_f32_16x16x32_bf16 v[62:65], v[158:161], v[162:165], v[62:65]
	v_mfma_f32_16x16x32_bf16 v[58:61], v[158:161], v[166:169], v[58:61]
	v_mfma_f32_16x16x32_bf16 v[54:57], v[158:161], v[234:237], v[54:57]
	v_mfma_f32_16x16x32_bf16 v[50:53], v[158:161], v[238:241], v[50:53]
	s_waitcnt lgkmcnt(0)
	v_mfma_f32_16x16x32_bf16 v[110:113], v[114:117], v[130:133], v[110:113]
	ds_read_b128 v[146:149], v226 offset:32768
	v_mfma_f32_16x16x32_bf16 v[106:109], v[114:117], v[134:137], v[106:109]
	ds_read_b128 v[150:153], v226 offset:34816
	v_mfma_f32_16x16x32_bf16 v[102:105], v[114:117], v[138:141], v[102:105]
	ds_read_b128 v[154:157], v226 offset:36864
	v_mfma_f32_16x16x32_bf16 v[98:101], v[114:117], v[142:145], v[98:101]
	ds_read_b128 v[158:161], v226 offset:38912
	v_mfma_f32_16x16x32_bf16 v[94:97], v[118:121], v[130:133], v[94:97]
	ds_read_b128 v[162:165], v230
	v_mfma_f32_16x16x32_bf16 v[90:93], v[118:121], v[134:137], v[90:93]
	ds_read_b128 v[166:169], v230 offset:2048
	v_mfma_f32_16x16x32_bf16 v[86:89], v[118:121], v[138:141], v[86:89]
	ds_read_b128 v[234:237], v230 offset:4096
	v_mfma_f32_16x16x32_bf16 v[82:85], v[118:121], v[142:145], v[82:85]
	ds_read_b128 v[238:241], v230 offset:6144
	v_mfma_f32_16x16x32_bf16 v[78:81], v[122:125], v[130:133], v[78:81]
	v_mfma_f32_16x16x32_bf16 v[74:77], v[122:125], v[134:137], v[74:77]
	v_mfma_f32_16x16x32_bf16 v[70:73], v[122:125], v[138:141], v[70:73]
	v_mfma_f32_16x16x32_bf16 v[66:69], v[122:125], v[142:145], v[66:69]
	v_mfma_f32_16x16x32_bf16 v[62:65], v[126:129], v[130:133], v[62:65]
	v_mfma_f32_16x16x32_bf16 v[58:61], v[126:129], v[134:137], v[58:61]
	v_mfma_f32_16x16x32_bf16 v[54:57], v[126:129], v[138:141], v[54:57]
	v_mfma_f32_16x16x32_bf16 v[50:53], v[126:129], v[142:145], v[50:53]
	s_add_i32 s13, s13, 2
	s_add_u32 s100, s100, 0x100
	s_addc_u32 s101, s101, 0
	s_add_u32 s98, s98, 0x100
	s_addc_u32 s99, s99, 0
	s_branch .Lmye_even
.Lmye_oddlast:
	v_mfma_f32_16x16x32_bf16 v[110:113], v[146:149], v[162:165], v[110:113]
	v_mfma_f32_16x16x32_bf16 v[106:109], v[146:149], v[166:169], v[106:109]
	v_mfma_f32_16x16x32_bf16 v[102:105], v[146:149], v[234:237], v[102:105]
	v_mfma_f32_16x16x32_bf16 v[98:101], v[146:149], v[238:241], v[98:101]
	v_mfma_f32_16x16x32_bf16 v[94:97], v[150:153], v[162:165], v[94:97]
	v_mfma_f32_16x16x32_bf16 v[90:93], v[150:153], v[166:169], v[90:93]
	v_mfma_f32_16x16x32_bf16 v[86:89], v[150:153], v[234:237], v[86:89]
	v_mfma_f32_16x16x32_bf16 v[82:85], v[150:153], v[238:241], v[82:85]
	v_mfma_f32_16x16x32_bf16 v[78:81], v[154:157], v[162:165], v[78:81]
	v_mfma_f32_16x16x32_bf16 v[74:77], v[154:157], v[166:169], v[74:77]
	v_mfma_f32_16x16x32_bf16 v[70:73], v[154:157], v[234:237], v[70:73]
	v_mfma_f32_16x16x32_bf16 v[66:69], v[154:157], v[238:241], v[66:69]
	v_mfma_f32_16x16x32_bf16 v[62:65], v[158:161], v[162:165], v[62:65]
	v_mfma_f32_16x16x32_bf16 v[58:61], v[158:161], v[166:169], v[58:61]
	v_mfma_f32_16x16x32_bf16 v[54:57], v[158:161], v[234:237], v[54:57]
	v_mfma_f32_16x16x32_bf16 v[50:53], v[158:161], v[238:241], v[50:53]
	s_waitcnt lgkmcnt(0)
	v_mfma_f32_16x16x32_bf16 v[110:113], v[114:117], v[130:133], v[110:113]
	ds_read_b128 v[146:149], v226 offset:32768
	v_mfma_f32_16x16x32_bf16 v[106:109], v[114:117], v[134:137], v[106:109]
	ds_read_b128 v[150:153], v226 offset:34816
	v_mfma_f32_16x16x32_bf16 v[102:105], v[114:117], v[138:141], v[102:105]
	ds_read_b128 v[154:157], v226 offset:36864
	v_mfma_f32_16x16x32_bf16 v[98:101], v[114:117], v[142:145], v[98:101]
	ds_read_b128 v[158:161], v226 offset:38912
	v_mfma_f32_16x16x32_bf16 v[94:97], v[118:121], v[130:133], v[94:97]
	ds_read_b128 v[162:165], v230
	v_mfma_f32_16x16x32_bf16 v[90:93], v[118:121], v[134:137], v[90:93]
	ds_read_b128 v[166:169], v230 offset:2048
	v_mfma_f32_16x16x32_bf16 v[86:89], v[118:121], v[138:141], v[86:89]
	ds_read_b128 v[234:237], v230 offset:4096
	v_mfma_f32_16x16x32_bf16 v[82:85], v[118:121], v[142:145], v[82:85]
	ds_read_b128 v[238:241], v230 offset:6144
	v_mfma_f32_16x16x32_bf16 v[78:81], v[122:125], v[130:133], v[78:81]
	v_mfma_f32_16x16x32_bf16 v[74:77], v[122:125], v[134:137], v[74:77]
	v_mfma_f32_16x16x32_bf16 v[70:73], v[122:125], v[138:141], v[70:73]
	v_mfma_f32_16x16x32_bf16 v[66:69], v[122:125], v[142:145], v[66:69]
	v_mfma_f32_16x16x32_bf16 v[62:65], v[126:129], v[130:133], v[62:65]
	v_mfma_f32_16x16x32_bf16 v[58:61], v[126:129], v[134:137], v[58:61]
	v_mfma_f32_16x16x32_bf16 v[54:57], v[126:129], v[138:141], v[54:57]
	v_mfma_f32_16x16x32_bf16 v[50:53], v[126:129], v[142:145], v[50:53]
	s_add_i32 s13, s13, 2
	s_add_u32 s100, s100, 0x100
	s_addc_u32 s101, s101, 0
	s_add_u32 s98, s98, 0x100
	s_addc_u32 s99, s99, 0
	s_waitcnt lgkmcnt(0)
	v_mfma_f32_16x16x32_bf16 v[110:113], v[146:149], v[162:165], v[110:113]
	v_mfma_f32_16x16x32_bf16 v[106:109], v[146:149], v[166:169], v[106:109]
	v_mfma_f32_16x16x32_bf16 v[102:105], v[146:149], v[234:237], v[102:105]
	v_mfma_f32_16x16x32_bf16 v[98:101], v[146:149], v[238:241], v[98:101]
	v_mfma_f32_16x16x32_bf16 v[94:97], v[150:153], v[162:165], v[94:97]
	v_mfma_f32_16x16x32_bf16 v[90:93], v[150:153], v[166:169], v[90:93]
	v_mfma_f32_16x16x32_bf16 v[86:89], v[150:153], v[234:237], v[86:89]
	v_mfma_f32_16x16x32_bf16 v[82:85], v[150:153], v[238:241], v[82:85]
	v_mfma_f32_16x16x32_bf16 v[78:81], v[154:157], v[162:165], v[78:81]
	v_mfma_f32_16x16x32_bf16 v[74:77], v[154:157], v[166:169], v[74:77]
	v_mfma_f32_16x16x32_bf16 v[70:73], v[154:157], v[234:237], v[70:73]
	v_mfma_f32_16x16x32_bf16 v[66:69], v[154:157], v[238:241], v[66:69]
	v_mfma_f32_16x16x32_bf16 v[62:65], v[158:161], v[162:165], v[62:65]
	v_mfma_f32_16x16x32_bf16 v[58:61], v[158:161], v[166:169], v[58:61]
	v_mfma_f32_16x16x32_bf16 v[54:57], v[158:161], v[234:237], v[54:57]
	v_mfma_f32_16x16x32_bf16 v[50:53], v[158:161], v[238:241], v[50:53]
	s_and_b64 vcc, exec, s[4:5]
	s_nop 7
	s_branch .LBB0_1359

.LBB0_1488:
	s_add_i32 s6, s19, s14
	s_mov_b32 s100, s6
	s_lshr_b32 s98, s100, 7
	s_lshl_b32 s98, s98, 10
	s_and_b32 s99, s100, 3
	s_lshl_b32 s99, s99, 8
	s_or_b32 s20, s98, s99
	s_lshl_b32 s98, s100, 5
	s_and_b32 s21, s98, 0xf80
	v_add_u32_e32 v48, s20, v171
	v_add_u32_e32 v50, s21, v171
	v_ashrrev_i32_e32 v49, 31, v48
	v_ashrrev_i32_e32 v51, 31, v50
	v_lshlrev_b64 v[48:49], 11, v[48:49]
	v_lshlrev_b64 v[50:51], 11, v[50:51]
	v_lshl_add_u64 v[48:49], v[176:177], 0, v[48:49]
	v_lshl_add_u64 v[50:51], v[178:179], 0, v[50:51]
	s_and_b64 vcc, exec, s[8:9]
	s_cbranch_vccnz .LBB0_1490
	s_waitcnt vmcnt(62)
	v_add_co_u32_e32 v4, vcc, 0x20000, v48
	s_nop 1
	v_addc_co_u32_e32 v5, vcc, 0, v49, vcc
	v_add_co_u32_e32 v8, vcc, 0x40000, v48
	s_nop 1
	v_addc_co_u32_e32 v9, vcc, 0, v49, vcc
	v_add_co_u32_e32 v12, vcc, 0x60000, v48
	s_nop 1
	v_addc_co_u32_e32 v13, vcc, 0, v49, vcc
	s_waitcnt vmcnt(0)
	v_add_co_u32_e32 v24, vcc, 0x20000, v50
	s_nop 1
	v_addc_co_u32_e32 v25, vcc, 0, v51, vcc
	global_load_dwordx4 v[36:39], v[48:49], off
	global_load_dwordx4 v[0:3], v[48:49], off offset:128
	global_load_dwordx4 v[44:47], v[4:5], off
	s_nop 0
	global_load_dwordx4 v[4:7], v[4:5], off offset:128
	s_nop 0
	global_load_dwordx4 v[32:35], v[8:9], off
	s_nop 0
	global_load_dwordx4 v[8:11], v[8:9], off offset:128
	s_nop 0
	global_load_dwordx4 v[40:43], v[12:13], off
	s_nop 0
	global_load_dwordx4 v[12:15], v[12:13], off offset:128
	s_nop 0
	global_load_dwordx4 v[20:23], v[50:51], off
	global_load_dwordx4 v[16:19], v[50:51], off offset:128
	global_load_dwordx4 v[28:31], v[24:25], off
	s_nop 0
	global_load_dwordx4 v[24:27], v[24:25], off offset:128
	s_waitcnt vmcnt(0)
.LBB0_1490:
	s_mov_b32 s6, s21
	v_add_u32_e32 v52, s6, v171
	v_ashrrev_i32_e32 v53, 31, v52
	s_mov_b32 s6, s20
	s_add_i32 s19, s19, s51
	v_lshlrev_b64 v[52:53], 11, v[52:53]
	s_cmpk_gt_u32 s19, 0xff
	s_nop 0
	v_add_u32_e32 v52, s6, v171
	s_cselect_b64 s[6:7], -1, 0
	s_add_i32 s12, s19, s14
	s_cmpk_lt_u32 s19, 0x100
	s_cselect_b64 s[8:9], -1, 0
	s_and_b64 s[10:11], s[8:9], exec
	s_cselect_b32 s10, s12, 0
	s_mov_b32 s100, s10
	s_lshr_b32 s98, s100, 7
	s_lshl_b32 s98, s98, 10
	s_and_b32 s99, s100, 3
	s_lshl_b32 s99, s99, 8
	s_or_b32 s11, s98, s99
	s_lshl_b32 s98, s100, 5
	s_and_b32 s10, s98, 0xf80
	v_add_u32_e32 v54, s10, v171
	s_mov_b32 s10, 0x20000
	s_barrier
	s_waitcnt vmcnt(8)
	ds_write_b128 v173, v[36:39]
	ds_write_b128 v173, v[44:47] offset:8192
	ds_write_b128 v173, v[32:35] offset:16384
	ds_write_b128 v173, v[40:43] offset:24576
	ds_write_b128 v214, v[20:23]
	ds_write_b128 v214, v[28:31] offset:8192
	v_add_co_u32_e32 v20, vcc, s10, v50
	v_ashrrev_i32_e32 v53, 31, v52
	s_nop 0
	v_addc_co_u32_e32 v21, vcc, 0, v51, vcc
	v_add_co_u32_e32 v32, vcc, 0x60000, v48
	global_load_dwordx4 v[28:31], v[20:21], off offset:256
	s_nop 0
	global_load_dwordx4 v[20:23], v[50:51], off offset:256
	v_addc_co_u32_e32 v33, vcc, 0, v49, vcc
	global_load_dwordx4 v[40:43], v[32:33], off offset:256
	v_add_co_u32_e32 v32, vcc, 0x40000, v48
	v_lshlrev_b64 v[52:53], 11, v[52:53]
	s_nop 0
	v_addc_co_u32_e32 v33, vcc, 0, v49, vcc
	v_add_co_u32_e32 v36, vcc, 0x20000, v48
	global_load_dwordx4 v[32:35], v[32:33], off offset:256
	s_nop 0
	v_addc_co_u32_e32 v37, vcc, 0, v49, vcc
	global_load_dwordx4 v[44:47], v[36:37], off offset:256
	s_nop 0
	global_load_dwordx4 v[36:39], v[48:49], off offset:256
	s_nop 0
	v_add_u32_e32 v52, s11, v171
	v_ashrrev_i32_e32 v53, 31, v52
	v_lshlrev_b64 v[52:53], 11, v[52:53]
	v_lshl_add_u64 v[186:187], v[176:177], 0, v[52:53]
	s_mov_b64 s[10:11], 0x40080
	v_ashrrev_i32_e32 v55, 31, v54
	v_lshl_add_u64 v[192:193], v[186:187], 0, s[10:11]
	s_mov_b64 s[10:11], 0x60080
	v_lshlrev_b64 v[54:55], 11, v[54:55]
	v_lshl_add_u64 v[194:195], v[186:187], 0, s[10:11]
	s_mov_b64 s[10:11], 0x40000
	v_lshl_add_u64 v[188:189], v[178:179], 0, v[54:55]
	v_lshl_add_u64 v[200:201], v[186:187], 0, s[10:11]
	s_mov_b64 s[10:11], 0x60000
	v_mov_b32_e32 v48, 0
	s_mov_b32 s22, 0
	v_lshl_add_u64 v[190:191], v[186:187], 0, s[0:1]
	v_lshl_add_u64 v[196:197], v[188:189], 0, s[0:1]
	v_lshl_add_u64 v[198:199], v[186:187], 0, s[2:3]
	v_lshl_add_u64 v[202:203], v[186:187], 0, s[10:11]
	v_lshl_add_u64 v[204:205], v[188:189], 0, s[2:3]
	v_mov_b32_e32 v49, v48
	v_mov_b32_e32 v50, v48
	v_mov_b32_e32 v51, v48
	v_mov_b32_e32 v52, v48
	v_mov_b32_e32 v53, v48
	v_mov_b32_e32 v54, v48
	v_mov_b32_e32 v55, v48
	v_mov_b32_e32 v56, v48
	v_mov_b32_e32 v57, v48
	v_mov_b32_e32 v58, v48
	v_mov_b32_e32 v59, v48
	v_mov_b32_e32 v60, v48
	v_mov_b32_e32 v61, v48
	v_mov_b32_e32 v62, v48
	v_mov_b32_e32 v63, v48
	v_mov_b32_e32 v64, v48
	v_mov_b32_e32 v65, v48
	v_mov_b32_e32 v66, v48
	v_mov_b32_e32 v67, v48
	v_mov_b32_e32 v68, v48
	v_mov_b32_e32 v69, v48
	v_mov_b32_e32 v70, v48
	v_mov_b32_e32 v71, v48
	v_mov_b32_e32 v72, v48
	v_mov_b32_e32 v73, v48
	v_mov_b32_e32 v74, v48
	v_mov_b32_e32 v75, v48
	v_mov_b32_e32 v76, v48
	v_mov_b32_e32 v77, v48
	v_mov_b32_e32 v78, v48
	v_mov_b32_e32 v79, v48
	v_mov_b32_e32 v80, v48
	v_mov_b32_e32 v81, v48
	v_mov_b32_e32 v82, v48
	v_mov_b32_e32 v83, v48
	v_mov_b32_e32 v84, v48
	v_mov_b32_e32 v85, v48
	v_mov_b32_e32 v86, v48
	v_mov_b32_e32 v87, v48
	v_mov_b32_e32 v88, v48
	v_mov_b32_e32 v89, v48
	v_mov_b32_e32 v90, v48
	v_mov_b32_e32 v91, v48
	v_mov_b32_e32 v92, v48
	v_mov_b32_e32 v93, v48
	v_mov_b32_e32 v94, v48
	v_mov_b32_e32 v95, v48
	v_mov_b32_e32 v96, v48
	v_mov_b32_e32 v97, v48
	v_mov_b32_e32 v98, v48
	v_mov_b32_e32 v99, v48
	v_mov_b32_e32 v100, v48
	v_mov_b32_e32 v101, v48
	v_mov_b32_e32 v102, v48
	v_mov_b32_e32 v103, v48
	v_mov_b32_e32 v104, v48
	v_mov_b32_e32 v105, v48
	v_mov_b32_e32 v106, v48
	v_mov_b32_e32 v107, v48
	v_mov_b32_e32 v108, v48
	v_mov_b32_e32 v109, v48
	v_mov_b32_e32 v110, v48
	v_mov_b32_e32 v111, v48
	s_lshl_b32 s98, s20, 11
	s_add_u32 s98, s76, s98
	s_addc_u32 s99, s77, 0
	s_add_u32 s98, s98, 0x2800000
	s_addc_u32 s99, s99, 0
	s_lshl_b32 s100, s21, 11
	s_add_u32 s100, s76, s100
	s_addc_u32 s101, s77, 0
	s_add_u32 s100, s100, 0x1800000
	s_addc_u32 s101, s101, 0
	v_lshl_add_u32 v184, v171, 11, v180
	v_add_u32_e32 v185, 0x20000, v184
	v_add_u32_e32 v182, 0x40000, v184
	v_add_u32_e32 v183, 0x60000, v184
	s_branch .LBB0_1492
.LBB0_1492:
	s_waitcnt lgkmcnt(0)
	s_barrier
	ds_read_b128 v[112:115], v215
	ds_read_b128 v[116:119], v215 offset:2048
	ds_read_b128 v[120:123], v215 offset:4096
	ds_read_b128 v[124:127], v215 offset:6144
	ds_read_b128 v[128:131], v216
	ds_read_b128 v[132:135], v216 offset:2048
	ds_read_b128 v[136:139], v216 offset:4096
	ds_read_b128 v[140:143], v216 offset:6144
	s_waitcnt vmcnt(14)
	ds_write_b128 v173, v[0:3] offset:32768
	ds_write_b128 v173, v[4:7] offset:40960
	ds_write_b128 v173, v[8:11] offset:49152
	ds_write_b128 v173, v[12:15] offset:57344
	ds_write_b128 v219, v[16:19]
	ds_write_b128 v219, v[24:27] offset:8192
	s_cmp_gt_u32 s22, 12
	s_mov_b64 s[10:11], -1
	s_cbranch_scc0 .Lmyffe__1496
	s_andn2_b64 vcc, exec, s[8:9]
	s_cbranch_vccnz .Lmyffe__1495
	global_load_dwordx4 v[4:7], v[190:191], off
	global_load_dwordx4 v[8:11], v[192:193], off
	global_load_dwordx4 v[0:3], v[186:187], off offset:128
	global_load_dwordx4 v[16:19], v[188:189], off offset:128
	global_load_dwordx4 v[12:15], v[194:195], off
	global_load_dwordx4 v[24:27], v[196:197], off

.Lmyffe__1496:
	s_andn2_b64 vcc, exec, s[10:11]
	s_cbranch_vccnz .Lmyffe__1498
	global_load_dwordx4 v[0:3], v184, s[98:99] offset:384
	global_load_dwordx4 v[4:7], v185, s[98:99] offset:384
	global_load_dwordx4 v[8:11], v182, s[98:99] offset:384
	global_load_dwordx4 v[12:15], v183, s[98:99] offset:384
	global_load_dwordx4 v[16:19], v184, s[100:101] offset:384
	global_load_dwordx4 v[24:27], v185, s[100:101] offset:384

.Lmyfso__1503:
	s_andn2_b64 vcc, exec, s[12:13]
	s_cbranch_vccnz .Lmyf_ocont
	global_load_dwordx4 v[36:39], v184, s[98:99] offset:512
	global_load_dwordx4 v[44:47], v185, s[98:99] offset:512
	global_load_dwordx4 v[32:35], v182, s[98:99] offset:512
	global_load_dwordx4 v[40:43], v183, s[98:99] offset:512
	global_load_dwordx4 v[20:23], v184, s[100:101] offset:512
	global_load_dwordx4 v[28:31], v185, s[100:101] offset:512
.Lmyf_ocont:
	v_mfma_f32_16x16x32_bf16 v[76:79], v[160:163], v[152:155], v[76:79]
	v_mfma_f32_16x16x32_bf16 v[72:75], v[164:167], v[152:155], v[72:75]
	v_mfma_f32_16x16x32_bf16 v[68:71], v[224:227], v[152:155], v[68:71]
	v_mfma_f32_16x16x32_bf16 v[64:67], v[228:231], v[152:155], v[64:67]
	v_mfma_f32_16x16x32_bf16 v[60:63], v[160:163], v[156:159], v[60:63]
	v_mfma_f32_16x16x32_bf16 v[56:59], v[164:167], v[156:159], v[56:59]
	v_mfma_f32_16x16x32_bf16 v[52:55], v[224:227], v[156:159], v[52:55]
	v_mfma_f32_16x16x32_bf16 v[48:51], v[228:231], v[156:159], v[48:51]
	s_waitcnt lgkmcnt(0)
	v_mfma_f32_16x16x32_bf16 v[108:111], v[128:131], v[112:115], v[108:111]
	ds_read_b128 v[144:147], v217 offset:32768
	v_mfma_f32_16x16x32_bf16 v[104:107], v[132:135], v[112:115], v[104:107]
	ds_read_b128 v[148:151], v217 offset:34816
	v_mfma_f32_16x16x32_bf16 v[100:103], v[136:139], v[112:115], v[100:103]
	ds_read_b128 v[152:155], v217 offset:36864
	v_mfma_f32_16x16x32_bf16 v[96:99], v[140:143], v[112:115], v[96:99]
	ds_read_b128 v[156:159], v217 offset:38912
	v_mfma_f32_16x16x32_bf16 v[92:95], v[128:131], v[116:119], v[92:95]
	ds_read_b128 v[160:163], v221
	v_mfma_f32_16x16x32_bf16 v[88:91], v[132:135], v[116:119], v[88:91]
	ds_read_b128 v[164:167], v221 offset:2048
	v_mfma_f32_16x16x32_bf16 v[84:87], v[136:139], v[116:119], v[84:87]
	ds_read_b128 v[224:227], v221 offset:4096
	v_mfma_f32_16x16x32_bf16 v[80:83], v[140:143], v[116:119], v[80:83]
	ds_read_b128 v[228:231], v221 offset:6144
	v_mfma_f32_16x16x32_bf16 v[76:79], v[128:131], v[120:123], v[76:79]
	v_mfma_f32_16x16x32_bf16 v[72:75], v[132:135], v[120:123], v[72:75]
	v_mfma_f32_16x16x32_bf16 v[68:71], v[136:139], v[120:123], v[68:71]
	v_mfma_f32_16x16x32_bf16 v[64:67], v[140:143], v[120:123], v[64:67]
	v_mfma_f32_16x16x32_bf16 v[60:63], v[128:131], v[124:127], v[60:63]
	v_mfma_f32_16x16x32_bf16 v[56:59], v[132:135], v[124:127], v[56:59]
	v_mfma_f32_16x16x32_bf16 v[52:55], v[136:139], v[124:127], v[52:55]
	v_mfma_f32_16x16x32_bf16 v[48:51], v[140:143], v[124:127], v[48:51]
	s_add_i32 s22, s22, 2
	s_add_u32 s100, s100, 0x100
	s_addc_u32 s101, s101, 0
	s_add_u32 s98, s98, 0x100
	s_addc_u32 s99, s99, 0
	s_branch .Lmyf_even
.Lmyf_oddlast:
	v_mfma_f32_16x16x32_bf16 v[108:111], v[160:163], v[144:147], v[108:111]
	v_mfma_f32_16x16x32_bf16 v[104:107], v[164:167], v[144:147], v[104:107]
	v_mfma_f32_16x16x32_bf16 v[100:103], v[224:227], v[144:147], v[100:103]
	v_mfma_f32_16x16x32_bf16 v[96:99], v[228:231], v[144:147], v[96:99]
	v_mfma_f32_16x16x32_bf16 v[92:95], v[160:163], v[148:151], v[92:95]
	v_mfma_f32_16x16x32_bf16 v[88:91], v[164:167], v[148:151], v[88:91]
	v_mfma_f32_16x16x32_bf16 v[84:87], v[224:227], v[148:151], v[84:87]
	v_mfma_f32_16x16x32_bf16 v[80:83], v[228:231], v[148:151], v[80:83]
	v_mfma_f32_16x16x32_bf16 v[76:79], v[160:163], v[152:155], v[76:79]
	v_mfma_f32_16x16x32_bf16 v[72:75], v[164:167], v[152:155], v[72:75]
	v_mfma_f32_16x16x32_bf16 v[68:71], v[224:227], v[152:155], v[68:71]
	v_mfma_f32_16x16x32_bf16 v[64:67], v[228:231], v[152:155], v[64:67]
	v_mfma_f32_16x16x32_bf16 v[60:63], v[160:163], v[156:159], v[60:63]
	v_mfma_f32_16x16x32_bf16 v[56:59], v[164:167], v[156:159], v[56:59]
	v_mfma_f32_16x16x32_bf16 v[52:55], v[224:227], v[156:159], v[52:55]
	v_mfma_f32_16x16x32_bf16 v[48:51], v[228:231], v[156:159], v[48:51]
	s_waitcnt lgkmcnt(0)
	v_mfma_f32_16x16x32_bf16 v[108:111], v[128:131], v[112:115], v[108:111]
	ds_read_b128 v[144:147], v217 offset:32768
	v_mfma_f32_16x16x32_bf16 v[104:107], v[132:135], v[112:115], v[104:107]
	ds_read_b128 v[148:151], v217 offset:34816
	v_mfma_f32_16x16x32_bf16 v[100:103], v[136:139], v[112:115], v[100:103]
	ds_read_b128 v[152:155], v217 offset:36864
	v_mfma_f32_16x16x32_bf16 v[96:99], v[140:143], v[112:115], v[96:99]
	ds_read_b128 v[156:159], v217 offset:38912
	v_mfma_f32_16x16x32_bf16 v[92:95], v[128:131], v[116:119], v[92:95]
	ds_read_b128 v[160:163], v221
	v_mfma_f32_16x16x32_bf16 v[88:91], v[132:135], v[116:119], v[88:91]
	ds_read_b128 v[164:167], v221 offset:2048
	v_mfma_f32_16x16x32_bf16 v[84:87], v[136:139], v[116:119], v[84:87]
	ds_read_b128 v[224:227], v221 offset:4096
	v_mfma_f32_16x16x32_bf16 v[80:83], v[140:143], v[116:119], v[80:83]
	ds_read_b128 v[228:231], v221 offset:6144
	v_mfma_f32_16x16x32_bf16 v[76:79], v[128:131], v[120:123], v[76:79]
	v_mfma_f32_16x16x32_bf16 v[72:75], v[132:135], v[120:123], v[72:75]
	v_mfma_f32_16x16x32_bf16 v[68:71], v[136:139], v[120:123], v[68:71]
	v_mfma_f32_16x16x32_bf16 v[64:67], v[140:143], v[120:123], v[64:67]
	v_mfma_f32_16x16x32_bf16 v[60:63], v[128:131], v[124:127], v[60:63]
	v_mfma_f32_16x16x32_bf16 v[56:59], v[132:135], v[124:127], v[56:59]
	v_mfma_f32_16x16x32_bf16 v[52:55], v[136:139], v[124:127], v[52:55]
	v_mfma_f32_16x16x32_bf16 v[48:51], v[140:143], v[124:127], v[48:51]
	s_add_i32 s22, s22, 2
	s_add_u32 s100, s100, 0x100
	s_addc_u32 s101, s101, 0
	s_add_u32 s98, s98, 0x100
	s_addc_u32 s99, s99, 0
	s_waitcnt lgkmcnt(0)
	v_mfma_f32_16x16x32_bf16 v[108:111], v[160:163], v[144:147], v[108:111]
	v_mfma_f32_16x16x32_bf16 v[104:107], v[164:167], v[144:147], v[104:107]
	v_mfma_f32_16x16x32_bf16 v[100:103], v[224:227], v[144:147], v[100:103]
	v_mfma_f32_16x16x32_bf16 v[96:99], v[228:231], v[144:147], v[96:99]
	v_mfma_f32_16x16x32_bf16 v[92:95], v[160:163], v[148:151], v[92:95]
	v_mfma_f32_16x16x32_bf16 v[88:91], v[164:167], v[148:151], v[88:91]
	v_mfma_f32_16x16x32_bf16 v[84:87], v[224:227], v[148:151], v[84:87]
	v_mfma_f32_16x16x32_bf16 v[80:83], v[228:231], v[148:151], v[80:83]
	v_mfma_f32_16x16x32_bf16 v[76:79], v[160:163], v[152:155], v[76:79]
	v_mfma_f32_16x16x32_bf16 v[72:75], v[164:167], v[152:155], v[72:75]
	v_mfma_f32_16x16x32_bf16 v[68:71], v[224:227], v[152:155], v[68:71]
	v_mfma_f32_16x16x32_bf16 v[64:67], v[228:231], v[152:155], v[64:67]
	v_mfma_f32_16x16x32_bf16 v[60:63], v[160:163], v[156:159], v[60:63]
	v_mfma_f32_16x16x32_bf16 v[56:59], v[164:167], v[156:159], v[56:59]
	v_mfma_f32_16x16x32_bf16 v[52:55], v[224:227], v[156:159], v[52:55]
	v_mfma_f32_16x16x32_bf16 v[48:51], v[228:231], v[156:159], v[48:51]
	s_and_b64 vcc, exec, s[10:11]
	s_nop 7
	s_branch .LBB0_1487

.LBB0_1562:
	s_and_b32 s6, s15, 0x380
	v_add_u32_e32 v52, s6, v173
	v_ashrrev_i32_e32 v53, 31, v52
	s_and_b32 s6, s16, 0x7fffff00
	s_add_i32 s62, s62, s51
	v_lshlrev_b64 v[52:53], 13, v[52:53]
	s_cmp_gt_u32 s62, 63
	s_nop 0
	v_add_u32_e32 v52, s6, v173
	s_cselect_b64 s[6:7], -1, 0
	s_add_i32 s12, s62, s14
	s_cmp_lt_u32 s62, 64
	s_cselect_b64 s[8:9], -1, 0
	s_and_b64 s[10:11], s[8:9], exec
	s_cselect_b32 s10, s12, 0
	s_lshl_b32 s11, s10, 5
	s_lshl_b32 s10, s10, 7
	s_and_b32 s10, s10, 0x380
	v_add_u32_e32 v54, s10, v173
	s_mov_b32 s10, 0x80000
	s_barrier
	s_waitcnt vmcnt(11)
	ds_write_b128 v204, v[0:3]
	s_waitcnt vmcnt(9)
	ds_write_b128 v204, v[12:15] offset:8192
	s_waitcnt vmcnt(0)
	ds_write_b128 v204, v[28:31] offset:16384
	ds_write_b128 v204, v[36:39] offset:24576
	ds_write_b128 v205, v[40:43]
	ds_write_b128 v205, v[44:47] offset:8192
	v_add_co_u32_e32 v12, vcc, s10, v50
	global_load_dwordx4 v[0:3], v[50:51], off offset:256
	s_nop 0
	v_addc_co_u32_e32 v13, vcc, 0, v51, vcc
	v_add_co_u32_e32 v28, vcc, 0x100000, v50
	global_load_dwordx4 v[12:15], v[12:13], off offset:256
	s_nop 0
	v_addc_co_u32_e32 v29, vcc, 0, v51, vcc
	v_add_co_u32_e32 v36, vcc, 0x180000, v50
	global_load_dwordx4 v[28:31], v[28:29], off offset:256
	s_nop 0
	v_addc_co_u32_e32 v37, vcc, 0, v51, vcc
	v_add_co_u32_e32 v44, vcc, 0x80000, v48
	global_load_dwordx4 v[36:39], v[36:37], off offset:256
	s_nop 0
	global_load_dwordx4 v[40:43], v[48:49], off offset:256
	v_addc_co_u32_e32 v45, vcc, 0, v49, vcc
	global_load_dwordx4 v[44:47], v[44:45], off offset:256
	v_ashrrev_i32_e32 v53, 31, v52
	v_lshlrev_b64 v[52:53], 13, v[52:53]
	s_and_b32 s11, s11, 0x7fffff00
	s_nop 0
	v_add_u32_e32 v52, s11, v173
	v_ashrrev_i32_e32 v53, 31, v52
	v_lshlrev_b64 v[52:53], 13, v[52:53]
	v_lshl_add_u64 v[184:185], v[176:177], 0, v[52:53]
	s_mov_b64 s[10:11], 0x100080
	v_ashrrev_i32_e32 v55, 31, v54
	v_lshl_add_u64 v[190:191], v[184:185], 0, s[10:11]
	s_mov_b64 s[10:11], 0x180080
	v_lshlrev_b64 v[52:53], 13, v[54:55]
	v_lshl_add_u64 v[192:193], v[184:185], 0, s[10:11]
	s_mov_b64 s[10:11], 0x100000
	v_lshl_add_u64 v[186:187], v[178:179], 0, v[52:53]
	v_lshl_add_u64 v[198:199], v[184:185], 0, s[10:11]
	s_mov_b64 s[10:11], 0x180000
	v_mov_b32_e32 v48, 0
	s_mov_b32 s19, 0
	v_lshl_add_u64 v[188:189], v[184:185], 0, s[0:1]
	v_lshl_add_u64 v[194:195], v[186:187], 0, s[0:1]
	v_lshl_add_u64 v[196:197], v[184:185], 0, s[2:3]
	v_lshl_add_u64 v[200:201], v[184:185], 0, s[10:11]
	v_lshl_add_u64 v[202:203], v[186:187], 0, s[2:3]
	v_mov_b32_e32 v49, v48
	v_mov_b32_e32 v50, v48
	v_mov_b32_e32 v51, v48
	v_mov_b32_e32 v52, v48
	v_mov_b32_e32 v53, v48
	v_mov_b32_e32 v54, v48
	v_mov_b32_e32 v55, v48
	v_mov_b32_e32 v56, v48
	v_mov_b32_e32 v57, v48
	v_mov_b32_e32 v58, v48
	v_mov_b32_e32 v59, v48
	v_mov_b32_e32 v60, v48
	v_mov_b32_e32 v61, v48
	v_mov_b32_e32 v62, v48
	v_mov_b32_e32 v63, v48
	v_mov_b32_e32 v64, v48
	v_mov_b32_e32 v65, v48
	v_mov_b32_e32 v66, v48
	v_mov_b32_e32 v67, v48
	v_mov_b32_e32 v68, v48
	v_mov_b32_e32 v69, v48
	v_mov_b32_e32 v70, v48
	v_mov_b32_e32 v71, v48
	v_mov_b32_e32 v72, v48
	v_mov_b32_e32 v73, v48
	v_mov_b32_e32 v74, v48
	v_mov_b32_e32 v75, v48
	v_mov_b32_e32 v76, v48
	v_mov_b32_e32 v77, v48
	v_mov_b32_e32 v78, v48
	v_mov_b32_e32 v79, v48
	v_mov_b32_e32 v80, v48
	v_mov_b32_e32 v81, v48
	v_mov_b32_e32 v82, v48
	v_mov_b32_e32 v83, v48
	v_mov_b32_e32 v84, v48
	v_mov_b32_e32 v85, v48
	v_mov_b32_e32 v86, v48
	v_mov_b32_e32 v87, v48
	v_mov_b32_e32 v88, v48
	v_mov_b32_e32 v89, v48
	v_mov_b32_e32 v90, v48
	v_mov_b32_e32 v91, v48
	v_mov_b32_e32 v92, v48
	v_mov_b32_e32 v93, v48
	v_mov_b32_e32 v94, v48
	v_mov_b32_e32 v95, v48
	v_mov_b32_e32 v96, v48
	v_mov_b32_e32 v97, v48
	v_mov_b32_e32 v98, v48
	v_mov_b32_e32 v99, v48
	v_mov_b32_e32 v100, v48
	v_mov_b32_e32 v101, v48
	v_mov_b32_e32 v102, v48
	v_mov_b32_e32 v103, v48
	v_mov_b32_e32 v104, v48
	v_mov_b32_e32 v105, v48
	v_mov_b32_e32 v106, v48
	v_mov_b32_e32 v107, v48
	v_mov_b32_e32 v108, v48
	v_mov_b32_e32 v109, v48
	v_mov_b32_e32 v110, v48
	v_mov_b32_e32 v111, v48
	s_lshl_b32 s98, s17, 13
	s_add_u32 s98, s76, s98
	s_addc_u32 s99, s77, 0
	s_add_u32 s98, s98, 0x4900000
	s_addc_u32 s99, s99, 0
	s_lshl_b32 s100, s18, 13
	s_add_u32 s100, s76, s100
	s_addc_u32 s101, s77, 0
	s_add_u32 s100, s100, 0x2000000
	s_addc_u32 s101, s101, 0
	v_lshl_add_u32 v182, v173, 13, v170
	v_add_u32_e32 v183, 0x80000, v182
	v_add_u32_e32 v180, 0x100000, v182
	v_add_u32_e32 v181, 0x180000, v182
	s_branch .LBB0_1564

.Lmygfe__1568:
	s_andn2_b64 vcc, exec, s[10:11]
	s_cbranch_vccnz .Lmygfe__1570
	global_load_dwordx4 v[4:7], v182, s[98:99] offset:384
	global_load_dwordx4 v[8:11], v183, s[98:99] offset:384
	global_load_dwordx4 v[16:19], v180, s[98:99] offset:384
	global_load_dwordx4 v[20:23], v181, s[98:99] offset:384
	global_load_dwordx4 v[24:27], v182, s[100:101] offset:384
	global_load_dwordx4 v[32:35], v183, s[100:101] offset:384

.Lmygso__1575:
	s_andn2_b64 vcc, exec, s[12:13]
	s_cbranch_vccnz .Lmyg_ocont
	global_load_dwordx4 v[0:3], v182, s[98:99] offset:512
	global_load_dwordx4 v[12:15], v183, s[98:99] offset:512
	global_load_dwordx4 v[28:31], v180, s[98:99] offset:512
	global_load_dwordx4 v[36:39], v181, s[98:99] offset:512
	global_load_dwordx4 v[40:43], v182, s[100:101] offset:512
	global_load_dwordx4 v[44:47], v183, s[100:101] offset:512
.Lmyg_ocont:
	v_mfma_f32_16x16x32_bf16 v[76:79], v[152:155], v[160:163], v[76:79]
	v_mfma_f32_16x16x32_bf16 v[72:75], v[152:155], v[164:167], v[72:75]
	v_mfma_f32_16x16x32_bf16 v[68:71], v[152:155], v[224:227], v[68:71]
	v_mfma_f32_16x16x32_bf16 v[64:67], v[152:155], v[228:231], v[64:67]
	v_mfma_f32_16x16x32_bf16 v[60:63], v[156:159], v[160:163], v[60:63]
	v_mfma_f32_16x16x32_bf16 v[56:59], v[156:159], v[164:167], v[56:59]
	v_mfma_f32_16x16x32_bf16 v[52:55], v[156:159], v[224:227], v[52:55]
	v_mfma_f32_16x16x32_bf16 v[48:51], v[156:159], v[228:231], v[48:51]
	s_waitcnt lgkmcnt(0)
	v_mfma_f32_16x16x32_bf16 v[108:111], v[112:115], v[128:131], v[108:111]
	ds_read_b128 v[144:147], v216 offset:32768
	v_mfma_f32_16x16x32_bf16 v[104:107], v[112:115], v[132:135], v[104:107]
	ds_read_b128 v[148:151], v216 offset:34816
	v_mfma_f32_16x16x32_bf16 v[100:103], v[112:115], v[136:139], v[100:103]
	ds_read_b128 v[152:155], v216 offset:36864
	v_mfma_f32_16x16x32_bf16 v[96:99], v[112:115], v[140:143], v[96:99]
	ds_read_b128 v[156:159], v216 offset:38912
	v_mfma_f32_16x16x32_bf16 v[92:95], v[116:119], v[128:131], v[92:95]
	ds_read_b128 v[160:163], v220
	v_mfma_f32_16x16x32_bf16 v[88:91], v[116:119], v[132:135], v[88:91]
	ds_read_b128 v[164:167], v220 offset:2048
	v_mfma_f32_16x16x32_bf16 v[84:87], v[116:119], v[136:139], v[84:87]
	ds_read_b128 v[224:227], v220 offset:4096
	v_mfma_f32_16x16x32_bf16 v[80:83], v[116:119], v[140:143], v[80:83]
	ds_read_b128 v[228:231], v220 offset:6144
	v_mfma_f32_16x16x32_bf16 v[76:79], v[120:123], v[128:131], v[76:79]
	v_mfma_f32_16x16x32_bf16 v[72:75], v[120:123], v[132:135], v[72:75]
	v_mfma_f32_16x16x32_bf16 v[68:71], v[120:123], v[136:139], v[68:71]
	v_mfma_f32_16x16x32_bf16 v[64:67], v[120:123], v[140:143], v[64:67]
	v_mfma_f32_16x16x32_bf16 v[60:63], v[124:127], v[128:131], v[60:63]
	v_mfma_f32_16x16x32_bf16 v[56:59], v[124:127], v[132:135], v[56:59]
	v_mfma_f32_16x16x32_bf16 v[52:55], v[124:127], v[136:139], v[52:55]
	v_mfma_f32_16x16x32_bf16 v[48:51], v[124:127], v[140:143], v[48:51]
	s_add_i32 s19, s19, 2
	s_add_u32 s100, s100, 0x100
	s_addc_u32 s101, s101, 0
	s_add_u32 s98, s98, 0x100
	s_addc_u32 s99, s99, 0
	s_branch .Lmyg_even
.Lmyg_oddlast:
	v_mfma_f32_16x16x32_bf16 v[108:111], v[144:147], v[160:163], v[108:111]
	v_mfma_f32_16x16x32_bf16 v[104:107], v[144:147], v[164:167], v[104:107]
	v_mfma_f32_16x16x32_bf16 v[100:103], v[144:147], v[224:227], v[100:103]
	v_mfma_f32_16x16x32_bf16 v[96:99], v[144:147], v[228:231], v[96:99]
	v_mfma_f32_16x16x32_bf16 v[92:95], v[148:151], v[160:163], v[92:95]
	v_mfma_f32_16x16x32_bf16 v[88:91], v[148:151], v[164:167], v[88:91]
	v_mfma_f32_16x16x32_bf16 v[84:87], v[148:151], v[224:227], v[84:87]
	v_mfma_f32_16x16x32_bf16 v[80:83], v[148:151], v[228:231], v[80:83]
	v_mfma_f32_16x16x32_bf16 v[76:79], v[152:155], v[160:163], v[76:79]
	v_mfma_f32_16x16x32_bf16 v[72:75], v[152:155], v[164:167], v[72:75]
	v_mfma_f32_16x16x32_bf16 v[68:71], v[152:155], v[224:227], v[68:71]
	v_mfma_f32_16x16x32_bf16 v[64:67], v[152:155], v[228:231], v[64:67]
	v_mfma_f32_16x16x32_bf16 v[60:63], v[156:159], v[160:163], v[60:63]
	v_mfma_f32_16x16x32_bf16 v[56:59], v[156:159], v[164:167], v[56:59]
	v_mfma_f32_16x16x32_bf16 v[52:55], v[156:159], v[224:227], v[52:55]
	v_mfma_f32_16x16x32_bf16 v[48:51], v[156:159], v[228:231], v[48:51]
	s_waitcnt lgkmcnt(0)
	v_mfma_f32_16x16x32_bf16 v[108:111], v[112:115], v[128:131], v[108:111]
	ds_read_b128 v[144:147], v216 offset:32768
	v_mfma_f32_16x16x32_bf16 v[104:107], v[112:115], v[132:135], v[104:107]
	ds_read_b128 v[148:151], v216 offset:34816
	v_mfma_f32_16x16x32_bf16 v[100:103], v[112:115], v[136:139], v[100:103]
	ds_read_b128 v[152:155], v216 offset:36864
	v_mfma_f32_16x16x32_bf16 v[96:99], v[112:115], v[140:143], v[96:99]
	ds_read_b128 v[156:159], v216 offset:38912
	v_mfma_f32_16x16x32_bf16 v[92:95], v[116:119], v[128:131], v[92:95]
	ds_read_b128 v[160:163], v220
	v_mfma_f32_16x16x32_bf16 v[88:91], v[116:119], v[132:135], v[88:91]
	ds_read_b128 v[164:167], v220 offset:2048
	v_mfma_f32_16x16x32_bf16 v[84:87], v[116:119], v[136:139], v[84:87]
	ds_read_b128 v[224:227], v220 offset:4096
	v_mfma_f32_16x16x32_bf16 v[80:83], v[116:119], v[140:143], v[80:83]
	ds_read_b128 v[228:231], v220 offset:6144
	v_mfma_f32_16x16x32_bf16 v[76:79], v[120:123], v[128:131], v[76:79]
	v_mfma_f32_16x16x32_bf16 v[72:75], v[120:123], v[132:135], v[72:75]
	v_mfma_f32_16x16x32_bf16 v[68:71], v[120:123], v[136:139], v[68:71]
	v_mfma_f32_16x16x32_bf16 v[64:67], v[120:123], v[140:143], v[64:67]
	v_mfma_f32_16x16x32_bf16 v[60:63], v[124:127], v[128:131], v[60:63]
	v_mfma_f32_16x16x32_bf16 v[56:59], v[124:127], v[132:135], v[56:59]
	v_mfma_f32_16x16x32_bf16 v[52:55], v[124:127], v[136:139], v[52:55]
	v_mfma_f32_16x16x32_bf16 v[48:51], v[124:127], v[140:143], v[48:51]
	s_add_i32 s19, s19, 2
	s_add_u32 s100, s100, 0x100
	s_addc_u32 s101, s101, 0
	s_add_u32 s98, s98, 0x100
	s_addc_u32 s99, s99, 0
	s_waitcnt lgkmcnt(0)
	v_mfma_f32_16x16x32_bf16 v[108:111], v[144:147], v[160:163], v[108:111]
	v_mfma_f32_16x16x32_bf16 v[104:107], v[144:147], v[164:167], v[104:107]
	v_mfma_f32_16x16x32_bf16 v[100:103], v[144:147], v[224:227], v[100:103]
	v_mfma_f32_16x16x32_bf16 v[96:99], v[144:147], v[228:231], v[96:99]
	v_mfma_f32_16x16x32_bf16 v[92:95], v[148:151], v[160:163], v[92:95]
	v_mfma_f32_16x16x32_bf16 v[88:91], v[148:151], v[164:167], v[88:91]
	v_mfma_f32_16x16x32_bf16 v[84:87], v[148:151], v[224:227], v[84:87]
	v_mfma_f32_16x16x32_bf16 v[80:83], v[148:151], v[228:231], v[80:83]
	v_mfma_f32_16x16x32_bf16 v[76:79], v[152:155], v[160:163], v[76:79]
	v_mfma_f32_16x16x32_bf16 v[72:75], v[152:155], v[164:167], v[72:75]
	v_mfma_f32_16x16x32_bf16 v[68:71], v[152:155], v[224:227], v[68:71]
	v_mfma_f32_16x16x32_bf16 v[64:67], v[152:155], v[228:231], v[64:67]
	v_mfma_f32_16x16x32_bf16 v[60:63], v[156:159], v[160:163], v[60:63]
	v_mfma_f32_16x16x32_bf16 v[56:59], v[156:159], v[164:167], v[56:59]
	v_mfma_f32_16x16x32_bf16 v[52:55], v[156:159], v[224:227], v[52:55]
	v_mfma_f32_16x16x32_bf16 v[48:51], v[156:159], v[228:231], v[48:51]
	s_and_b64 vcc, exec, s[10:11]
	s_nop 7
	s_branch .LBB0_1559

	.amdhsa_kernel _Z14fwd_megakernel6Params
		.amdhsa_group_segment_fixed_size 16
		.amdhsa_private_segment_fixed_size 0
		.amdhsa_kernarg_size 488
		.amdhsa_user_sgpr_count 2
		.amdhsa_user_sgpr_dispatch_ptr 0
		.amdhsa_user_sgpr_queue_ptr 0
		.amdhsa_user_sgpr_kernarg_segment_ptr 1
		.amdhsa_user_sgpr_dispatch_id 0
		.amdhsa_user_sgpr_kernarg_preload_length 0
		.amdhsa_user_sgpr_kernarg_preload_offset 0
		.amdhsa_user_sgpr_private_segment_size 0
		.amdhsa_uses_dynamic_stack 0
		.amdhsa_enable_private_segment 0
		.amdhsa_system_sgpr_workgroup_id_x 1
		.amdhsa_system_sgpr_workgroup_id_y 0
		.amdhsa_system_sgpr_workgroup_id_z 0
		.amdhsa_system_sgpr_workgroup_info 0
		.amdhsa_system_vgpr_workitem_id 2
		.amdhsa_next_free_vgpr 256
		.amdhsa_next_free_sgpr 102
		.amdhsa_accum_offset 256
		.amdhsa_reserve_vcc 1
		.amdhsa_float_round_mode_32 0
		.amdhsa_float_round_mode_16_64 0
		.amdhsa_float_denorm_mode_32 3
		.amdhsa_float_denorm_mode_16_64 3
		.amdhsa_dx10_clamp 1
		.amdhsa_ieee_mode 1
		.amdhsa_fp16_overflow 0
		.amdhsa_tg_split 0
		.amdhsa_exception_fp_ieee_invalid_op 0
		.amdhsa_exception_fp_denorm_src 0
		.amdhsa_exception_fp_ieee_div_zero 0
		.amdhsa_exception_fp_ieee_overflow 0
		.amdhsa_exception_fp_ieee_underflow 0
		.amdhsa_exception_fp_ieee_inexact 0
		.amdhsa_exception_int_div_zero 0
	.end_amdhsa_kernel

amdhsa.kernels:
  - .agpr_count:     0
    .args:
      - .offset:         0
        .size:           232
        .value_kind:     by_value
      - .offset:         232
        .size:           4
        .value_kind:     hidden_block_count_x
      - .offset:         236
        .size:           4
        .value_kind:     hidden_block_count_y
      - .offset:         240
        .size:           4
        .value_kind:     hidden_block_count_z
      - .offset:         244
        .size:           2
        .value_kind:     hidden_group_size_x
      - .offset:         246
        .size:           2
        .value_kind:     hidden_group_size_y
      - .offset:         248
        .size:           2
        .value_kind:     hidden_group_size_z
      - .offset:         250
        .size:           2
        .value_kind:     hidden_remainder_x
      - .offset:         252
        .size:           2
        .value_kind:     hidden_remainder_y
      - .offset:         254
        .size:           2
        .value_kind:     hidden_remainder_z
      - .offset:         272
        .size:           8
        .value_kind:     hidden_global_offset_x
      - .offset:         280
        .size:           8
        .value_kind:     hidden_global_offset_y
      - .offset:         288
        .size:           8
        .value_kind:     hidden_global_offset_z
      - .offset:         296
        .size:           2
        .value_kind:     hidden_grid_dims
      - .offset:         320
        .size:           8
        .value_kind:     hidden_multigrid_sync_arg
      - .offset:         352
        .size:           4
        .value_kind:     hidden_dynamic_lds_size
    .group_segment_fixed_size: 16
    .kernarg_segment_align: 8
    .kernarg_segment_size: 488
    .language:       OpenCL C
    .language_version:
      - 2
      - 0
    .max_flat_workgroup_size: 512
    .name:           _Z14fwd_megakernel6Params
    .private_segment_fixed_size: 0
    .sgpr_count:     108
    .sgpr_spill_count: 278
    .symbol:         _Z14fwd_megakernel6Params.kd
    .uniform_work_group_size: 1
    .uses_dynamic_stack: false
    .vgpr_count:     256
    .vgpr_spill_count: 0
    .wavefront_size: 64
